# row-statistics exchanges: 50 ds_bpermute + wait reduction steps replaced by v_permlane16/32_swap (same two-operand sums)
# speedup vs baseline: 1.0011x; 1.0011x over previous
;     __device__ __forceinline__ bool run(const f32x4 (&v)[2][2][4][2], const Unit& u, int wr, int wc, int fr, int fq, PG8_LAS unsigned char* lds, int wid, int lane) const {
;     ...
;             for (int m = 0; m < 4; ++m) {
;                 float s = 0.f;
; #pragma unroll
;                 for (int bj = 0; bj < 2; ++bj)
; #pragma unroll
;                     for (int n = 0; n < 2; ++n) { const f32x4 x = v[ai][bj][m][n]; s += (x[0] + x[1]) + (x[2] + x[3]); }
;                 s += __shfl_xor(s, 16); s += __shfl_xor(s, 32);
;                 const float mw = s * (1.0f / 64.0f); float q = 0.f;
; #pragma unroll
;                 for (int bj = 0; bj < 2; ++bj)
; #pragma unroll
;                     for (int n = 0; n < 2; ++n) { const f32x4 d = v[ai][bj][m][n] - mw; q += (d[0] * d[0] + d[1] * d[1]) + (d[2] * d[2] + d[3] * d[3]); }
;                 q += __shfl_xor(q, 16); q += __shfl_xor(q, 32);
;                 if (fq == 0) P[(ai * HALF + wr * 64 + m * 16 + fr) * 4 + wc] = (f32x2v){mw, q};
.LBB0_1035:
	s_or_b64 exec, exec, s[0:1]
	v_mov_b32_e32 v150, v111
	v_mov_b32_e32 v151, v112
	v_mov_b32_e32 v154, v110
	v_mov_b32_e32 v155, v113
	v_pk_add_f32 v[150:151], v[150:151], v[154:155]
	v_mov_b32_e32 v154, v107
	v_mov_b32_e32 v155, v108
	v_mov_b32_e32 v156, v106
	v_mov_b32_e32 v157, v109
	v_pk_add_f32 v[154:155], v[154:155], v[156:157]
	v_add_f32_e32 v150, v150, v151
	v_pk_add_f32 v[154:155], v[154:155], v[154:155] op_sel_hi:[0,1]
	v_add_f32_e32 v151, 0, v150
	v_add_f32_e32 v157, v102, v103
	v_add_f32_e32 v159, v104, v105
	v_mov_b32_e32 v156, v98
	v_mov_b32_e32 v158, v99
	v_mov_b32_e32 v154, v100
	v_mov_b32_e32 v150, v101
	v_pk_add_f32 v[156:157], v[156:157], v[158:159]
	v_pk_add_f32 v[150:151], v[154:155], v[150:151]
	v_mov_b32_e32 v155, v111
	v_pk_add_f32 v[150:151], v[156:157], v[150:151]
	v_mov_b32_e32 v154, v110
	v_add_f32_e32 v150, v150, v151
	ds_bpermute_b32 v151, v171, v150
	v_mov_b32_e32 v156, v107
	s_waitcnt lgkmcnt(0)
	v_add_f32_e32 v150, v150, v151
	v_mov_b32_e32 v151, v150
	s_nop 1
	v_permlane32_swap_b32 v150, v151
	s_waitcnt lgkmcnt(0)
	v_add_f32_e32 v150, v150, v151
	v_fmamk_f32 v153, v150, 0xbc800000, v113
	v_fmac_f32_e32 v155, 0xbc800000, v150
	v_fmamk_f32 v151, v150, 0xbc800000, v112
	v_fmac_f32_e32 v154, 0xbc800000, v150
	v_mul_f32_e32 v155, v155, v155
	v_mul_f32_e32 v153, v153, v153
	v_fmac_f32_e32 v155, v154, v154
	v_fmac_f32_e32 v153, v151, v151
	v_add_f32_e32 v151, v155, v153
	v_fmamk_f32 v154, v150, 0xbc800000, v109
	v_mov_b32_e32 v155, v106
	v_fmac_f32_e32 v156, 0xbc800000, v150
	v_fmamk_f32 v153, v150, 0xbc800000, v108
	v_fmac_f32_e32 v155, 0xbc800000, v150
	v_mul_f32_e32 v156, v156, v156
	v_mul_f32_e32 v154, v154, v154
	v_fmac_f32_e32 v156, v155, v155
	v_fmac_f32_e32 v154, v153, v153
	v_add_f32_e32 v153, v156, v154
	v_mov_b32_e32 v156, v103
	v_fmamk_f32 v154, v150, 0xbc800000, v105
	v_mov_b32_e32 v155, v102
	v_fmac_f32_e32 v156, 0xbc800000, v150
	v_add_f32_e32 v151, v151, v153
	v_fmamk_f32 v153, v150, 0xbc800000, v104
	v_fmac_f32_e32 v155, 0xbc800000, v150
	v_mul_f32_e32 v156, v156, v156
	v_mul_f32_e32 v154, v154, v154
	v_fmac_f32_e32 v156, v155, v155
	v_fmac_f32_e32 v154, v153, v153
	v_add_f32_e32 v153, v156, v154
	v_mov_b32_e32 v156, v99
	v_fmamk_f32 v154, v150, 0xbc800000, v101
	v_mov_b32_e32 v155, v98
	v_fmac_f32_e32 v156, 0xbc800000, v150
	v_add_f32_e32 v151, v153, v151
	v_fmamk_f32 v153, v150, 0xbc800000, v100
	v_fmac_f32_e32 v155, 0xbc800000, v150
	v_mul_f32_e32 v156, v156, v156
	v_mul_f32_e32 v154, v154, v154
	v_fmac_f32_e32 v156, v155, v155
	v_fmac_f32_e32 v154, v153, v153
	v_add_f32_e32 v153, v156, v154
	v_add_f32_e32 v151, v153, v151
	v_mov_b32_e32 v153, v151
	s_nop 1
	v_permlane16_swap_b32 v151, v153
	s_waitcnt lgkmcnt(0)
	v_add_f32_e32 v151, v151, v153
	ds_bpermute_b32 v153, v172, v151
	s_and_saveexec_b64 s[0:1], s[4:5]
	s_cbranch_execz .LBB0_1037
	s_lshl_b32 s3, s52, 11
	s_add_i32 s3, s29, s3
	v_mul_f32_e32 v150, 0x3c800000, v150
	v_lshl_add_u32 v154, v170, 5, s3
	s_waitcnt lgkmcnt(0)
	v_add_f32_e32 v151, v151, v153
	ds_write_b64 v154, v[150:151] offset:512
.LBB0_1037:
	s_or_b64 exec, exec, s[0:1]
	v_mov_b32_e32 v150, v95
	v_mov_b32_e32 v151, v96
	v_mov_b32_e32 v154, v94
	v_mov_b32_e32 v155, v97
	v_pk_add_f32 v[150:151], v[150:151], v[154:155]
	v_mov_b32_e32 v154, v91
	v_mov_b32_e32 v155, v92
	v_mov_b32_e32 v156, v90
	v_mov_b32_e32 v157, v93
	v_pk_add_f32 v[154:155], v[154:155], v[156:157]
	v_add_f32_e32 v150, v150, v151
	v_pk_add_f32 v[154:155], v[154:155], v[154:155] op_sel_hi:[0,1]
	v_add_f32_e32 v151, 0, v150
	v_add_f32_e32 v157, v86, v87
	v_add_f32_e32 v159, v88, v89
	v_mov_b32_e32 v156, v82
	v_mov_b32_e32 v158, v83
	v_mov_b32_e32 v154, v84
	v_mov_b32_e32 v150, v85
	v_pk_add_f32 v[156:157], v[156:157], v[158:159]
	v_pk_add_f32 v[150:151], v[154:155], v[150:151]
	v_mov_b32_e32 v155, v95
	v_pk_add_f32 v[150:151], v[156:157], v[150:151]
	v_mov_b32_e32 v154, v94
	v_add_f32_e32 v150, v150, v151
	ds_bpermute_b32 v151, v171, v150
	v_mov_b32_e32 v156, v91
	s_waitcnt lgkmcnt(0)
	v_add_f32_e32 v150, v150, v151
	v_mov_b32_e32 v151, v150
	s_nop 1
	v_permlane32_swap_b32 v150, v151
	s_waitcnt lgkmcnt(0)
	v_add_f32_e32 v150, v150, v151
	v_fmamk_f32 v153, v150, 0xbc800000, v97
	v_fmac_f32_e32 v155, 0xbc800000, v150
	v_fmamk_f32 v151, v150, 0xbc800000, v96
	v_fmac_f32_e32 v154, 0xbc800000, v150
	v_mul_f32_e32 v155, v155, v155
	v_mul_f32_e32 v153, v153, v153
	v_fmac_f32_e32 v155, v154, v154
	v_fmac_f32_e32 v153, v151, v151
	v_add_f32_e32 v151, v155, v153
	v_fmamk_f32 v154, v150, 0xbc800000, v93
	v_mov_b32_e32 v155, v90
	v_fmac_f32_e32 v156, 0xbc800000, v150
	v_fmamk_f32 v153, v150, 0xbc800000, v92
	v_fmac_f32_e32 v155, 0xbc800000, v150
	v_mul_f32_e32 v156, v156, v156
	v_mul_f32_e32 v154, v154, v154
	v_fmac_f32_e32 v156, v155, v155
	v_fmac_f32_e32 v154, v153, v153
	v_add_f32_e32 v153, v156, v154
	v_mov_b32_e32 v156, v87
	v_fmamk_f32 v154, v150, 0xbc800000, v89
	v_mov_b32_e32 v155, v86
	v_fmac_f32_e32 v156, 0xbc800000, v150
	v_add_f32_e32 v151, v151, v153
	v_fmamk_f32 v153, v150, 0xbc800000, v88
	v_fmac_f32_e32 v155, 0xbc800000, v150
	v_mul_f32_e32 v156, v156, v156
	v_mul_f32_e32 v154, v154, v154
	v_fmac_f32_e32 v156, v155, v155
	v_fmac_f32_e32 v154, v153, v153
	v_add_f32_e32 v153, v156, v154
	v_mov_b32_e32 v156, v83
	v_fmamk_f32 v154, v150, 0xbc800000, v85
	v_mov_b32_e32 v155, v82
	v_fmac_f32_e32 v156, 0xbc800000, v150
	v_add_f32_e32 v151, v153, v151
	v_fmamk_f32 v153, v150, 0xbc800000, v84
	v_fmac_f32_e32 v155, 0xbc800000, v150
	v_mul_f32_e32 v156, v156, v156
	v_mul_f32_e32 v154, v154, v154
	v_fmac_f32_e32 v156, v155, v155
	v_fmac_f32_e32 v154, v153, v153
	v_add_f32_e32 v153, v156, v154
	v_add_f32_e32 v151, v153, v151
	v_mov_b32_e32 v153, v151
	s_nop 1
	v_permlane16_swap_b32 v151, v153
	s_waitcnt lgkmcnt(0)
	v_add_f32_e32 v151, v151, v153
	ds_bpermute_b32 v153, v172, v151
	s_and_saveexec_b64 s[0:1], s[4:5]
	s_cbranch_execz .LBB0_1039
	s_lshl_b32 s3, s52, 11
	s_add_i32 s3, s29, s3
	v_mul_f32_e32 v150, 0x3c800000, v150
	v_lshl_add_u32 v154, v170, 5, s3
	s_waitcnt lgkmcnt(0)
	v_add_f32_e32 v151, v151, v153
	ds_write_b64 v154, v[150:151] offset:1024
;     __device__ __forceinline__ bool run(const f32x4 (&v)[2][2][4][2], const Unit& u, int wr, int wc, int fr, int fq, PG8_LAS unsigned char* lds, int wid, int lane) const {
;     ...
;             for (int m = 0; m < 4; ++m) {
;                 float s = 0.f;
; #pragma unroll
;                 for (int bj = 0; bj < 2; ++bj)
; #pragma unroll
;                     for (int n = 0; n < 2; ++n) { const f32x4 x = v[ai][bj][m][n]; s += (x[0] + x[1]) + (x[2] + x[3]); }
;                 s += __shfl_xor(s, 16); s += __shfl_xor(s, 32);
;                 const float mw = s * (1.0f / 64.0f); float q = 0.f;
; #pragma unroll
;                 for (int bj = 0; bj < 2; ++bj)
; #pragma unroll
;                     for (int n = 0; n < 2; ++n) { const f32x4 d = v[ai][bj][m][n] - mw; q += (d[0] * d[0] + d[1] * d[1]) + (d[2] * d[2] + d[3] * d[3]); }
;                 q += __shfl_xor(q, 16); q += __shfl_xor(q, 32);
;                 if (fq == 0) P[(ai * HALF + wr * 64 + m * 16 + fr) * 4 + wc] = (f32x2v){mw, q};
.LBB0_1039:
	s_or_b64 exec, exec, s[0:1]
	v_mov_b32_e32 v150, v79
	v_mov_b32_e32 v151, v80
	v_mov_b32_e32 v154, v78
	v_mov_b32_e32 v155, v81
	v_pk_add_f32 v[150:151], v[150:151], v[154:155]
	v_mov_b32_e32 v154, v75
	v_mov_b32_e32 v155, v76
	v_mov_b32_e32 v156, v74
	v_mov_b32_e32 v157, v77
	v_pk_add_f32 v[154:155], v[154:155], v[156:157]
	v_add_f32_e32 v150, v150, v151
	v_pk_add_f32 v[154:155], v[154:155], v[154:155] op_sel_hi:[0,1]
	v_add_f32_e32 v151, 0, v150
	v_add_f32_e32 v157, v70, v71
	v_add_f32_e32 v159, v72, v73
	v_mov_b32_e32 v156, v66
	v_mov_b32_e32 v158, v67
	v_mov_b32_e32 v154, v68
	v_mov_b32_e32 v150, v69
	v_pk_add_f32 v[156:157], v[156:157], v[158:159]
	v_pk_add_f32 v[150:151], v[154:155], v[150:151]
	v_mov_b32_e32 v155, v79
	v_pk_add_f32 v[150:151], v[156:157], v[150:151]
	v_mov_b32_e32 v154, v78
	v_add_f32_e32 v150, v150, v151
	ds_bpermute_b32 v151, v171, v150
	v_mov_b32_e32 v156, v75
	s_waitcnt lgkmcnt(0)
	v_add_f32_e32 v150, v150, v151
	v_mov_b32_e32 v151, v150
	s_nop 1
	v_permlane32_swap_b32 v150, v151
	s_waitcnt lgkmcnt(0)
	v_add_f32_e32 v150, v150, v151
	v_fmamk_f32 v153, v150, 0xbc800000, v81
	v_fmac_f32_e32 v155, 0xbc800000, v150
	v_fmamk_f32 v151, v150, 0xbc800000, v80
	v_fmac_f32_e32 v154, 0xbc800000, v150
	v_mul_f32_e32 v155, v155, v155
	v_mul_f32_e32 v153, v153, v153
	v_fmac_f32_e32 v155, v154, v154
	v_fmac_f32_e32 v153, v151, v151
	v_add_f32_e32 v151, v155, v153
	v_fmamk_f32 v154, v150, 0xbc800000, v77
	v_mov_b32_e32 v155, v74
	v_fmac_f32_e32 v156, 0xbc800000, v150
	v_fmamk_f32 v153, v150, 0xbc800000, v76
	v_fmac_f32_e32 v155, 0xbc800000, v150
	v_mul_f32_e32 v156, v156, v156
	v_mul_f32_e32 v154, v154, v154
	v_fmac_f32_e32 v156, v155, v155
	v_fmac_f32_e32 v154, v153, v153
	v_add_f32_e32 v153, v156, v154
	v_mov_b32_e32 v156, v71
	v_fmamk_f32 v154, v150, 0xbc800000, v73
	v_mov_b32_e32 v155, v70
	v_fmac_f32_e32 v156, 0xbc800000, v150
	v_add_f32_e32 v151, v151, v153
	v_fmamk_f32 v153, v150, 0xbc800000, v72
	v_fmac_f32_e32 v155, 0xbc800000, v150
	v_mul_f32_e32 v156, v156, v156
	v_mul_f32_e32 v154, v154, v154
	v_fmac_f32_e32 v156, v155, v155
	v_fmac_f32_e32 v154, v153, v153
	v_add_f32_e32 v153, v156, v154
	v_mov_b32_e32 v156, v67
	v_fmamk_f32 v154, v150, 0xbc800000, v69
	v_mov_b32_e32 v155, v66
	v_fmac_f32_e32 v156, 0xbc800000, v150
	v_add_f32_e32 v151, v153, v151
	v_fmamk_f32 v153, v150, 0xbc800000, v68
	v_fmac_f32_e32 v155, 0xbc800000, v150
	v_mul_f32_e32 v156, v156, v156
	v_mul_f32_e32 v154, v154, v154
	v_fmac_f32_e32 v156, v155, v155
	v_fmac_f32_e32 v154, v153, v153
	v_add_f32_e32 v153, v156, v154
	v_add_f32_e32 v151, v153, v151
	v_mov_b32_e32 v153, v151
	s_nop 1
	v_permlane16_swap_b32 v151, v153
	s_waitcnt lgkmcnt(0)
	v_add_f32_e32 v151, v151, v153
	ds_bpermute_b32 v153, v172, v151
	s_and_saveexec_b64 s[0:1], s[4:5]
	s_cbranch_execz .LBB0_1041
	s_lshl_b32 s3, s52, 11
	s_add_i32 s3, s29, s3
	v_mul_f32_e32 v150, 0x3c800000, v150
	v_lshl_add_u32 v154, v170, 5, s3
	s_waitcnt lgkmcnt(0)
	v_add_f32_e32 v151, v151, v153
	ds_write_b64 v154, v[150:151] offset:1536
.LBB0_1041:
	s_or_b64 exec, exec, s[0:1]
	v_mov_b32_e32 v150, v63
	v_mov_b32_e32 v151, v64
	v_mov_b32_e32 v154, v62
	v_mov_b32_e32 v155, v65
	v_pk_add_f32 v[150:151], v[150:151], v[154:155]
	v_mov_b32_e32 v154, v59
	v_mov_b32_e32 v155, v60
	v_mov_b32_e32 v156, v58
	v_mov_b32_e32 v157, v61
	v_pk_add_f32 v[154:155], v[154:155], v[156:157]
	v_add_f32_e32 v150, v150, v151
	v_pk_add_f32 v[154:155], v[154:155], v[154:155] op_sel_hi:[0,1]
	v_add_f32_e32 v151, 0, v150
	v_add_f32_e32 v157, v54, v55
	v_add_f32_e32 v159, v56, v57
	v_mov_b32_e32 v156, v50
	v_mov_b32_e32 v158, v51
	v_mov_b32_e32 v154, v52
	v_mov_b32_e32 v150, v53
	v_pk_add_f32 v[156:157], v[156:157], v[158:159]
	v_pk_add_f32 v[150:151], v[154:155], v[150:151]
	v_mov_b32_e32 v155, v63
	v_pk_add_f32 v[150:151], v[156:157], v[150:151]
	v_mov_b32_e32 v154, v62
	v_add_f32_e32 v150, v150, v151
	ds_bpermute_b32 v151, v171, v150
	v_mov_b32_e32 v156, v59
	s_waitcnt lgkmcnt(0)
	v_add_f32_e32 v150, v150, v151
	v_mov_b32_e32 v151, v150
	s_nop 1
	v_permlane32_swap_b32 v150, v151
	s_waitcnt lgkmcnt(0)
	v_add_f32_e32 v150, v150, v151
	v_fmamk_f32 v153, v150, 0xbc800000, v65
	v_fmac_f32_e32 v155, 0xbc800000, v150
	v_fmamk_f32 v151, v150, 0xbc800000, v64
	v_fmac_f32_e32 v154, 0xbc800000, v150
	v_mul_f32_e32 v155, v155, v155
	v_mul_f32_e32 v153, v153, v153
	v_fmac_f32_e32 v155, v154, v154
	v_fmac_f32_e32 v153, v151, v151
	v_add_f32_e32 v151, v155, v153
	v_fmamk_f32 v154, v150, 0xbc800000, v61
	v_mov_b32_e32 v155, v58
	v_fmac_f32_e32 v156, 0xbc800000, v150
	v_fmamk_f32 v153, v150, 0xbc800000, v60
	v_fmac_f32_e32 v155, 0xbc800000, v150
	v_mul_f32_e32 v156, v156, v156
	v_mul_f32_e32 v154, v154, v154
	v_fmac_f32_e32 v156, v155, v155
	v_fmac_f32_e32 v154, v153, v153
	v_add_f32_e32 v153, v156, v154
	v_mov_b32_e32 v156, v55
	v_fmamk_f32 v154, v150, 0xbc800000, v57
	v_mov_b32_e32 v155, v54
	v_fmac_f32_e32 v156, 0xbc800000, v150
	v_add_f32_e32 v151, v151, v153
	v_fmamk_f32 v153, v150, 0xbc800000, v56
	v_fmac_f32_e32 v155, 0xbc800000, v150
	v_mul_f32_e32 v156, v156, v156
	v_mul_f32_e32 v154, v154, v154
	v_fmac_f32_e32 v156, v155, v155
	v_fmac_f32_e32 v154, v153, v153
	v_add_f32_e32 v153, v156, v154
	v_mov_b32_e32 v156, v51
	v_fmamk_f32 v154, v150, 0xbc800000, v53
	v_mov_b32_e32 v155, v50
	v_fmac_f32_e32 v156, 0xbc800000, v150
	v_add_f32_e32 v151, v153, v151
	v_fmamk_f32 v153, v150, 0xbc800000, v52
	v_fmac_f32_e32 v155, 0xbc800000, v150
	v_mul_f32_e32 v156, v156, v156
	v_mul_f32_e32 v154, v154, v154
	v_fmac_f32_e32 v156, v155, v155
	v_fmac_f32_e32 v154, v153, v153
	v_add_f32_e32 v153, v156, v154
	v_add_f32_e32 v151, v153, v151
	v_mov_b32_e32 v153, v151
	s_nop 1
	v_permlane16_swap_b32 v151, v153
	s_waitcnt lgkmcnt(0)
	v_add_f32_e32 v151, v151, v153
	ds_bpermute_b32 v153, v172, v151
	s_and_saveexec_b64 s[0:1], s[4:5]
	s_cbranch_execz .LBB0_1043
	s_lshl_b32 s3, s52, 11
	s_add_i32 s3, s29, s3
	v_mul_f32_e32 v150, 0x3c800000, v150
	v_lshl_add_u32 v154, v170, 5, s3
	s_waitcnt lgkmcnt(0)
	v_add_f32_e32 v151, v151, v153
	ds_write_b64 v154, v[150:151] offset:4096
;     __device__ __forceinline__ bool run(const f32x4 (&v)[2][2][4][2], const Unit& u, int wr, int wc, int fr, int fq, PG8_LAS unsigned char* lds, int wid, int lane) const {
;     ...
;             for (int m = 0; m < 4; ++m) {
;                 float s = 0.f;
; #pragma unroll
;                 for (int bj = 0; bj < 2; ++bj)
; #pragma unroll
;                     for (int n = 0; n < 2; ++n) { const f32x4 x = v[ai][bj][m][n]; s += (x[0] + x[1]) + (x[2] + x[3]); }
;                 s += __shfl_xor(s, 16); s += __shfl_xor(s, 32);
;                 const float mw = s * (1.0f / 64.0f); float q = 0.f;
; #pragma unroll
;                 for (int bj = 0; bj < 2; ++bj)
; #pragma unroll
;                     for (int n = 0; n < 2; ++n) { const f32x4 d = v[ai][bj][m][n] - mw; q += (d[0] * d[0] + d[1] * d[1]) + (d[2] * d[2] + d[3] * d[3]); }
;                 q += __shfl_xor(q, 16); q += __shfl_xor(q, 32);
;                 if (fq == 0) P[(ai * HALF + wr * 64 + m * 16 + fr) * 4 + wc] = (f32x2v){mw, q};
.LBB0_1043:
	s_or_b64 exec, exec, s[0:1]
	v_mov_b32_e32 v150, v47
	v_mov_b32_e32 v151, v48
	v_mov_b32_e32 v154, v46
	v_mov_b32_e32 v155, v49
	v_pk_add_f32 v[150:151], v[150:151], v[154:155]
	v_mov_b32_e32 v154, v43
	v_mov_b32_e32 v155, v44
	v_mov_b32_e32 v156, v42
	v_mov_b32_e32 v157, v45
	v_pk_add_f32 v[154:155], v[154:155], v[156:157]
	v_add_f32_e32 v150, v150, v151
	v_pk_add_f32 v[154:155], v[154:155], v[154:155] op_sel_hi:[0,1]
	v_add_f32_e32 v151, 0, v150
	v_add_f32_e32 v157, v38, v39
	v_add_f32_e32 v159, v40, v41
	v_mov_b32_e32 v156, v34
	v_mov_b32_e32 v158, v35
	v_mov_b32_e32 v154, v36
	v_mov_b32_e32 v150, v37
	v_pk_add_f32 v[156:157], v[156:157], v[158:159]
	v_pk_add_f32 v[150:151], v[154:155], v[150:151]
	v_mov_b32_e32 v155, v47
	v_pk_add_f32 v[150:151], v[156:157], v[150:151]
	v_mov_b32_e32 v154, v46
	v_add_f32_e32 v150, v150, v151
	ds_bpermute_b32 v151, v171, v150
	v_mov_b32_e32 v156, v43
	s_waitcnt lgkmcnt(0)
	v_add_f32_e32 v150, v150, v151
	v_mov_b32_e32 v151, v150
	s_nop 1
	v_permlane32_swap_b32 v150, v151
	s_waitcnt lgkmcnt(0)
	v_add_f32_e32 v150, v150, v151
	v_fmamk_f32 v153, v150, 0xbc800000, v49
	v_fmac_f32_e32 v155, 0xbc800000, v150
	v_fmamk_f32 v151, v150, 0xbc800000, v48
	v_fmac_f32_e32 v154, 0xbc800000, v150
	v_mul_f32_e32 v155, v155, v155
	v_mul_f32_e32 v153, v153, v153
	v_fmac_f32_e32 v155, v154, v154
	v_fmac_f32_e32 v153, v151, v151
	v_add_f32_e32 v151, v155, v153
	v_fmamk_f32 v154, v150, 0xbc800000, v45
	v_mov_b32_e32 v155, v42
	v_fmac_f32_e32 v156, 0xbc800000, v150
	v_fmamk_f32 v153, v150, 0xbc800000, v44
	v_fmac_f32_e32 v155, 0xbc800000, v150
	v_mul_f32_e32 v156, v156, v156
	v_mul_f32_e32 v154, v154, v154
	v_fmac_f32_e32 v156, v155, v155
	v_fmac_f32_e32 v154, v153, v153
	v_add_f32_e32 v153, v156, v154
	v_mov_b32_e32 v156, v39
	v_fmamk_f32 v154, v150, 0xbc800000, v41
	v_mov_b32_e32 v155, v38
	v_fmac_f32_e32 v156, 0xbc800000, v150
	v_add_f32_e32 v151, v151, v153
	v_fmamk_f32 v153, v150, 0xbc800000, v40
	v_fmac_f32_e32 v155, 0xbc800000, v150
	v_mul_f32_e32 v156, v156, v156
	v_mul_f32_e32 v154, v154, v154
	v_fmac_f32_e32 v156, v155, v155
	v_fmac_f32_e32 v154, v153, v153
	v_add_f32_e32 v153, v156, v154
	v_mov_b32_e32 v156, v35
	v_fmamk_f32 v154, v150, 0xbc800000, v37
	v_mov_b32_e32 v155, v34
	v_fmac_f32_e32 v156, 0xbc800000, v150
	v_add_f32_e32 v151, v153, v151
	v_fmamk_f32 v153, v150, 0xbc800000, v36
	v_fmac_f32_e32 v155, 0xbc800000, v150
	v_mul_f32_e32 v156, v156, v156
	v_mul_f32_e32 v154, v154, v154
	v_fmac_f32_e32 v156, v155, v155
	v_fmac_f32_e32 v154, v153, v153
	v_add_f32_e32 v153, v156, v154
	v_add_f32_e32 v151, v153, v151
	v_mov_b32_e32 v153, v151
	s_nop 1
	v_permlane16_swap_b32 v151, v153
	s_waitcnt lgkmcnt(0)
	v_add_f32_e32 v151, v151, v153
	ds_bpermute_b32 v153, v172, v151
	s_and_saveexec_b64 s[0:1], s[4:5]
	s_cbranch_execz .LBB0_1045
	s_lshl_b32 s3, s52, 11
	s_add_i32 s3, s29, s3
	v_mul_f32_e32 v150, 0x3c800000, v150
	v_lshl_add_u32 v154, v170, 5, s3
	s_waitcnt lgkmcnt(0)
	v_add_f32_e32 v151, v151, v153
	ds_write_b64 v154, v[150:151] offset:4608
;     __device__ __forceinline__ bool run(const f32x4 (&v)[2][2][4][2], const Unit& u, int wr, int wc, int fr, int fq, PG8_LAS unsigned char* lds, int wid, int lane) const {
;     ...
;             for (int m = 0; m < 4; ++m) {
;                 float s = 0.f;
; #pragma unroll
;                 for (int bj = 0; bj < 2; ++bj)
; #pragma unroll
;                     for (int n = 0; n < 2; ++n) { const f32x4 x = v[ai][bj][m][n]; s += (x[0] + x[1]) + (x[2] + x[3]); }
;                 s += __shfl_xor(s, 16); s += __shfl_xor(s, 32);
;                 const float mw = s * (1.0f / 64.0f); float q = 0.f;
; #pragma unroll
;                 for (int bj = 0; bj < 2; ++bj)
; #pragma unroll
;                     for (int n = 0; n < 2; ++n) { const f32x4 d = v[ai][bj][m][n] - mw; q += (d[0] * d[0] + d[1] * d[1]) + (d[2] * d[2] + d[3] * d[3]); }
;                 q += __shfl_xor(q, 16); q += __shfl_xor(q, 32);
;                 if (fq == 0) P[(ai * HALF + wr * 64 + m * 16 + fr) * 4 + wc] = (f32x2v){mw, q};
.LBB0_1045:
	s_or_b64 exec, exec, s[0:1]
	v_mov_b32_e32 v150, v31
	v_mov_b32_e32 v151, v32
	v_mov_b32_e32 v154, v30
	v_mov_b32_e32 v155, v33
	v_pk_add_f32 v[150:151], v[150:151], v[154:155]
	v_mov_b32_e32 v154, v27
	v_mov_b32_e32 v155, v28
	v_mov_b32_e32 v156, v26
	v_mov_b32_e32 v157, v29
	v_pk_add_f32 v[154:155], v[154:155], v[156:157]
	v_add_f32_e32 v150, v150, v151
	v_pk_add_f32 v[154:155], v[154:155], v[154:155] op_sel_hi:[0,1]
	v_add_f32_e32 v151, 0, v150
	v_add_f32_e32 v157, v22, v23
	v_add_f32_e32 v159, v24, v25
	v_mov_b32_e32 v156, v18
	v_mov_b32_e32 v158, v19
	v_mov_b32_e32 v154, v20
	v_mov_b32_e32 v150, v21
	v_pk_add_f32 v[156:157], v[156:157], v[158:159]
	v_pk_add_f32 v[150:151], v[154:155], v[150:151]
	v_mov_b32_e32 v155, v31
	v_pk_add_f32 v[150:151], v[156:157], v[150:151]
	v_mov_b32_e32 v154, v30
	v_add_f32_e32 v150, v150, v151
	ds_bpermute_b32 v151, v171, v150
	v_mov_b32_e32 v156, v27
	s_waitcnt lgkmcnt(0)
	v_add_f32_e32 v150, v150, v151
	v_mov_b32_e32 v151, v150
	s_nop 1
	v_permlane32_swap_b32 v150, v151
	s_waitcnt lgkmcnt(0)
	v_add_f32_e32 v150, v150, v151
	v_fmamk_f32 v153, v150, 0xbc800000, v33
	v_fmac_f32_e32 v155, 0xbc800000, v150
	v_fmamk_f32 v151, v150, 0xbc800000, v32
	v_fmac_f32_e32 v154, 0xbc800000, v150
	v_mul_f32_e32 v155, v155, v155
	v_mul_f32_e32 v153, v153, v153
	v_fmac_f32_e32 v155, v154, v154
	v_fmac_f32_e32 v153, v151, v151
	v_add_f32_e32 v151, v155, v153
	v_fmamk_f32 v154, v150, 0xbc800000, v29
	v_mov_b32_e32 v155, v26
	v_fmac_f32_e32 v156, 0xbc800000, v150
	v_fmamk_f32 v153, v150, 0xbc800000, v28
	v_fmac_f32_e32 v155, 0xbc800000, v150
	v_mul_f32_e32 v156, v156, v156
	v_mul_f32_e32 v154, v154, v154
	v_fmac_f32_e32 v156, v155, v155
	v_fmac_f32_e32 v154, v153, v153
	v_add_f32_e32 v153, v156, v154
	v_mov_b32_e32 v156, v23
	v_fmamk_f32 v154, v150, 0xbc800000, v25
	v_mov_b32_e32 v155, v22
	v_fmac_f32_e32 v156, 0xbc800000, v150
	v_add_f32_e32 v151, v151, v153
	v_fmamk_f32 v153, v150, 0xbc800000, v24
	v_fmac_f32_e32 v155, 0xbc800000, v150
	v_mul_f32_e32 v156, v156, v156
	v_mul_f32_e32 v154, v154, v154
	v_fmac_f32_e32 v156, v155, v155
	v_fmac_f32_e32 v154, v153, v153
	v_add_f32_e32 v153, v156, v154
	v_mov_b32_e32 v156, v19
	v_fmamk_f32 v154, v150, 0xbc800000, v21
	v_mov_b32_e32 v155, v18
	v_fmac_f32_e32 v156, 0xbc800000, v150
	v_add_f32_e32 v151, v153, v151
	v_fmamk_f32 v153, v150, 0xbc800000, v20
	v_fmac_f32_e32 v155, 0xbc800000, v150
	v_mul_f32_e32 v156, v156, v156
	v_mul_f32_e32 v154, v154, v154
	v_fmac_f32_e32 v156, v155, v155
	v_fmac_f32_e32 v154, v153, v153
	v_add_f32_e32 v153, v156, v154
	v_add_f32_e32 v151, v153, v151
	v_mov_b32_e32 v153, v151
	s_nop 1
	v_permlane16_swap_b32 v151, v153
	s_waitcnt lgkmcnt(0)
	v_add_f32_e32 v151, v151, v153
	ds_bpermute_b32 v153, v172, v151
	s_and_saveexec_b64 s[0:1], s[4:5]
	s_cbranch_execz .LBB0_1047
	s_lshl_b32 s3, s52, 11
	s_add_i32 s3, s29, s3
	v_mul_f32_e32 v150, 0x3c800000, v150
	v_lshl_add_u32 v154, v170, 5, s3
	s_waitcnt lgkmcnt(0)
	v_add_f32_e32 v151, v151, v153
	ds_write_b64 v154, v[150:151] offset:5120
.LBB0_1047:
	s_or_b64 exec, exec, s[0:1]
	v_mov_b32_e32 v150, v15
	v_mov_b32_e32 v151, v16
	v_mov_b32_e32 v154, v14
	v_mov_b32_e32 v155, v17
	v_pk_add_f32 v[150:151], v[150:151], v[154:155]
	v_mov_b32_e32 v154, v11
	v_mov_b32_e32 v155, v12
	v_mov_b32_e32 v156, v10
	v_mov_b32_e32 v157, v13
	v_pk_add_f32 v[154:155], v[154:155], v[156:157]
	v_add_f32_e32 v150, v150, v151
	v_pk_add_f32 v[154:155], v[154:155], v[154:155] op_sel_hi:[0,1]
	v_add_f32_e32 v151, 0, v150
	v_add_f32_e32 v157, v6, v7
	v_add_f32_e32 v159, v8, v9
	v_mov_b32_e32 v156, v2
	v_mov_b32_e32 v158, v3
	v_mov_b32_e32 v154, v4
	v_mov_b32_e32 v150, v5
	v_pk_add_f32 v[156:157], v[156:157], v[158:159]
	v_pk_add_f32 v[150:151], v[154:155], v[150:151]
	v_mov_b32_e32 v155, v15
	v_pk_add_f32 v[150:151], v[156:157], v[150:151]
	v_mov_b32_e32 v154, v14
	v_add_f32_e32 v150, v150, v151
	ds_bpermute_b32 v151, v171, v150
	v_mov_b32_e32 v156, v11
	s_waitcnt lgkmcnt(0)
	v_add_f32_e32 v150, v150, v151
	v_mov_b32_e32 v151, v150
	s_nop 1
	v_permlane32_swap_b32 v150, v151
	s_waitcnt lgkmcnt(0)
	v_add_f32_e32 v150, v150, v151
	v_fmamk_f32 v153, v150, 0xbc800000, v17
	v_fmac_f32_e32 v155, 0xbc800000, v150
	v_fmamk_f32 v151, v150, 0xbc800000, v16
	v_fmac_f32_e32 v154, 0xbc800000, v150
	v_mul_f32_e32 v155, v155, v155
	v_mul_f32_e32 v153, v153, v153
	v_fmac_f32_e32 v155, v154, v154
	v_fmac_f32_e32 v153, v151, v151
	v_add_f32_e32 v151, v155, v153
	v_fmamk_f32 v154, v150, 0xbc800000, v13
	v_mov_b32_e32 v155, v10
	v_fmac_f32_e32 v156, 0xbc800000, v150
	v_fmamk_f32 v153, v150, 0xbc800000, v12
	v_fmac_f32_e32 v155, 0xbc800000, v150
	v_mul_f32_e32 v156, v156, v156
	v_mul_f32_e32 v154, v154, v154
	v_fmac_f32_e32 v156, v155, v155
	v_fmac_f32_e32 v154, v153, v153
	v_add_f32_e32 v153, v156, v154
	v_mov_b32_e32 v156, v7
	v_fmamk_f32 v154, v150, 0xbc800000, v9
	v_mov_b32_e32 v155, v6
	v_fmac_f32_e32 v156, 0xbc800000, v150
	v_add_f32_e32 v151, v151, v153
	v_fmamk_f32 v153, v150, 0xbc800000, v8
	v_fmac_f32_e32 v155, 0xbc800000, v150
	v_mul_f32_e32 v156, v156, v156
	v_mul_f32_e32 v154, v154, v154
	v_fmac_f32_e32 v156, v155, v155
	v_fmac_f32_e32 v154, v153, v153
	v_add_f32_e32 v153, v156, v154
	v_mov_b32_e32 v156, v3
	v_fmamk_f32 v154, v150, 0xbc800000, v5
	v_mov_b32_e32 v155, v2
	v_fmac_f32_e32 v156, 0xbc800000, v150
	v_add_f32_e32 v151, v153, v151
	v_fmamk_f32 v153, v150, 0xbc800000, v4
	v_fmac_f32_e32 v155, 0xbc800000, v150
	v_mul_f32_e32 v156, v156, v156
	v_mul_f32_e32 v154, v154, v154
	v_fmac_f32_e32 v156, v155, v155
	v_fmac_f32_e32 v154, v153, v153
	v_add_f32_e32 v153, v156, v154
	v_add_f32_e32 v151, v153, v151
	v_mov_b32_e32 v153, v151
	s_nop 1
	v_permlane16_swap_b32 v151, v153
	s_waitcnt lgkmcnt(0)
	v_add_f32_e32 v151, v151, v153
	ds_bpermute_b32 v153, v172, v151
	s_and_saveexec_b64 s[0:1], s[4:5]
	s_cbranch_execz .LBB0_1049
	s_lshl_b32 s3, s52, 11
	s_add_i32 s3, s29, s3
	v_mul_f32_e32 v150, 0x3c800000, v150
	v_lshl_add_u32 v154, v170, 5, s3
	s_waitcnt lgkmcnt(0)
	v_add_f32_e32 v151, v151, v153
	ds_write_b64 v154, v[150:151] offset:5632

;     __device__ __forceinline__ void fused(f32x4 (&acc)[2][2][4][2], const Unit& u, int wr, int wc, int fr, int fq, PG8_LAS unsigned char* lds, int wid, int lane) const {
;     ...
;         for (int ai = 0; ai < 2; ++ai)
; #pragma unroll
;             for (int m = 0; m < 4; ++m) { const int r = ai * HALF + wr * 64 + m * 16 + fr; const f32x2v sr = S[r]; const size_t off = (size_t)(u.pm * BM + r) * ldc + col0;
; #pragma unroll
;                 for (int bj = 0; bj < 2; ++bj)
; #pragma unroll
;                     for (int n = 0; n < 2; ++n) { const f32x4 bs = *(const f32x4*)(base + off + bj * HALF + n * 16); acc[ai][bj][m][n] = bs + cvv[bj][n] * (acc[ai][bj][m][n] * sr.y); }
;                 asm volatile("" : "+v"(acc[ai][0][m][0]), "+v"(acc[ai][0][m][1]), "+v"(acc[ai][1][m][0]), "+v"(acc[ai][1][m][1]));
;                 if (m & 1) asm volatile("" ::: "memory"); }
.LBB0_1073:
	s_or_b64 exec, exec, s[0:1]
	v_add_u32_e32 v150, s3, v152
	v_readlane_b32 s36, v240, 11
	v_ashrrev_i32_e32 v151, 31, v150
	v_readlane_b32 s37, v240, 12
	v_lshlrev_b64 v[154:155], 12, v[150:151]
	s_mov_b64 s[0:1], s[36:37]
	v_lshl_add_u64 v[154:155], s[0:1], 0, v[154:155]
	v_lshlrev_b64 v[168:169], 2, v[162:163]
	s_waitcnt lgkmcnt(0)
	s_barrier
	v_lshl_add_u64 v[174:175], v[154:155], 0, v[168:169]
	global_load_dwordx4 v[154:157], v[174:175], off
	global_load_dwordx4 v[158:161], v[174:175], off offset:64
	global_load_dwordx4 v[164:167], v[174:175], off offset:512
	s_nop 0
	global_load_dwordx4 v[174:177], v[174:175], off offset:576
	v_lshl_add_u32 v182, v152, 3, 0
	ds_read_b64 v[178:179], v182 offset:8192
	v_add_u32_e32 v152, 16, v150
	s_waitcnt lgkmcnt(0)
	v_ashrrev_i32_e32 v153, 31, v152
	v_lshlrev_b64 v[180:181], 12, v[152:153]
	v_lshl_add_u64 v[180:181], s[0:1], 0, v[180:181]
	v_pk_mul_f32 v[128:129], v[128:129], v[178:179] op_sel:[0,1]
	v_pk_mul_f32 v[126:127], v[126:127], v[178:179] op_sel:[0,1]
	v_pk_mul_f32 v[124:125], v[124:125], v[178:179] op_sel:[0,1]
	v_pk_mul_f32 v[122:123], v[122:123], v[178:179] op_sel:[0,1]
	v_pk_mul_f32 v[186:187], v[120:121], v[178:179] op_sel:[0,1]
	v_pk_mul_f32 v[188:189], v[118:119], v[178:179] op_sel:[0,1]
	v_pk_mul_f32 v[190:191], v[116:117], v[178:179] op_sel:[0,1]
	v_pk_mul_f32 v[178:179], v[114:115], v[178:179] op_sel:[0,1]
	v_lshl_add_u64 v[180:181], v[180:181], 0, v[168:169]
	v_readlane_b32 s38, v240, 13
	v_readlane_b32 s39, v240, 14
	v_readlane_b32 s40, v240, 15
	v_readlane_b32 s41, v240, 16
	v_readlane_b32 s42, v240, 17
	v_readlane_b32 s43, v240, 18
	v_readlane_b32 s44, v240, 19
	v_readlane_b32 s45, v240, 20
	v_readlane_b32 s46, v240, 21
	v_readlane_b32 s47, v240, 22
	v_readlane_b32 s48, v240, 23
	v_readlane_b32 s49, v240, 24
	v_readlane_b32 s50, v240, 25
	v_readlane_b32 s51, v240, 26
	s_waitcnt vmcnt(0)
	v_pk_fma_f32 v[114:115], v[142:143], v[126:127], v[154:155]
	v_pk_fma_f32 v[116:117], v[144:145], v[128:129], v[156:157]
	v_pk_fma_f32 v[118:119], v[138:139], v[122:123], v[158:159]
	v_pk_fma_f32 v[120:121], v[140:141], v[124:125], v[160:161]
	v_pk_fma_f32 v[122:123], v[134:135], v[188:189], v[164:165]
	v_pk_fma_f32 v[124:125], v[136:137], v[186:187], v[166:167]
	v_pk_fma_f32 v[126:127], v[130:131], v[178:179], v[174:175]
	v_pk_fma_f32 v[128:129], v[132:133], v[190:191], v[176:177]
	v_add_u32_e32 v154, 32, v150
	global_load_dwordx4 v[156:159], v[180:181], off
	global_load_dwordx4 v[164:167], v[180:181], off offset:64
	global_load_dwordx4 v[174:177], v[180:181], off offset:512
	s_nop 0
	global_load_dwordx4 v[178:181], v[180:181], off offset:576
	ds_read_b64 v[160:161], v182 offset:8320
	v_ashrrev_i32_e32 v155, 31, v154
	v_lshlrev_b64 v[186:187], 12, v[154:155]
	v_lshl_add_u64 v[186:187], s[0:1], 0, v[186:187]
	v_lshl_add_u64 v[186:187], v[186:187], 0, v[168:169]
	s_waitcnt lgkmcnt(0)
	v_pk_mul_f32 v[112:113], v[112:113], v[160:161] op_sel:[0,1]
	v_pk_mul_f32 v[110:111], v[110:111], v[160:161] op_sel:[0,1]
	v_pk_mul_f32 v[108:109], v[108:109], v[160:161] op_sel:[0,1]
	v_pk_mul_f32 v[106:107], v[106:107], v[160:161] op_sel:[0,1]
	v_pk_mul_f32 v[104:105], v[104:105], v[160:161] op_sel:[0,1]
	v_pk_mul_f32 v[102:103], v[102:103], v[160:161] op_sel:[0,1]
	v_pk_mul_f32 v[100:101], v[100:101], v[160:161] op_sel:[0,1]
	v_pk_mul_f32 v[98:99], v[98:99], v[160:161] op_sel:[0,1]
	v_mov_b32_e32 v196, v114
	v_mov_b32_e32 v197, v117
	v_mov_b32_e32 v198, v119
	v_mov_b32_e32 v199, v120
	v_mov_b32_e32 v200, v118
	v_mov_b32_e32 v201, v121
	v_add_f32_e32 v203, v122, v123
	v_add_f32_e32 v207, v124, v125
	v_mov_b32_e32 v202, v126
	v_mov_b32_e32 v206, v127
	v_mov_b32_e32 v208, v129
	s_waitcnt vmcnt(3)
	v_pk_fma_f32 v[110:111], v[142:143], v[110:111], v[156:157]
	v_pk_fma_f32 v[112:113], v[144:145], v[112:113], v[158:159]
	s_waitcnt vmcnt(2)
	v_pk_fma_f32 v[106:107], v[138:139], v[106:107], v[164:165]
	v_pk_fma_f32 v[108:109], v[140:141], v[108:109], v[166:167]
	s_waitcnt vmcnt(1)
	v_pk_fma_f32 v[102:103], v[134:135], v[102:103], v[174:175]
	v_pk_fma_f32 v[104:105], v[136:137], v[104:105], v[176:177]
	s_waitcnt vmcnt(0)
	v_pk_fma_f32 v[98:99], v[130:131], v[98:99], v[178:179]
	v_pk_fma_f32 v[100:101], v[132:133], v[100:101], v[180:181]
	v_add_u32_e32 v156, 48, v150
	global_load_dwordx4 v[158:161], v[186:187], off
	global_load_dwordx4 v[164:167], v[186:187], off offset:64
	global_load_dwordx4 v[174:177], v[186:187], off offset:512
	global_load_dwordx4 v[178:181], v[186:187], off offset:576
	ds_read_b64 v[186:187], v182 offset:8448
	v_ashrrev_i32_e32 v157, 31, v156
	v_lshlrev_b64 v[188:189], 12, v[156:157]
	v_lshl_add_u64 v[188:189], s[0:1], 0, v[188:189]
	v_lshl_add_u64 v[188:189], v[188:189], 0, v[168:169]
	s_waitcnt lgkmcnt(0)
	v_pk_mul_f32 v[96:97], v[96:97], v[186:187] op_sel:[0,1]
	v_pk_mul_f32 v[94:95], v[94:95], v[186:187] op_sel:[0,1]
	v_pk_mul_f32 v[92:93], v[92:93], v[186:187] op_sel:[0,1]
	v_pk_mul_f32 v[90:91], v[90:91], v[186:187] op_sel:[0,1]
	v_pk_mul_f32 v[88:89], v[88:89], v[186:187] op_sel:[0,1]
	v_pk_mul_f32 v[86:87], v[86:87], v[186:187] op_sel:[0,1]
	v_pk_mul_f32 v[84:85], v[84:85], v[186:187] op_sel:[0,1]
	v_pk_mul_f32 v[82:83], v[82:83], v[186:187] op_sel:[0,1]
	s_waitcnt vmcnt(3)
	v_pk_fma_f32 v[94:95], v[142:143], v[94:95], v[158:159]
	v_pk_fma_f32 v[96:97], v[144:145], v[96:97], v[160:161]
	s_waitcnt vmcnt(2)
	v_pk_fma_f32 v[90:91], v[138:139], v[90:91], v[164:165]
	v_pk_fma_f32 v[92:93], v[140:141], v[92:93], v[166:167]
	s_waitcnt vmcnt(1)
	v_pk_fma_f32 v[86:87], v[134:135], v[86:87], v[174:175]
	v_pk_fma_f32 v[88:89], v[136:137], v[88:89], v[176:177]
	s_waitcnt vmcnt(0)
;     __device__ __forceinline__ void fused(f32x4 (&acc)[2][2][4][2], const Unit& u, int wr, int wc, int fr, int fq, PG8_LAS unsigned char* lds, int wid, int lane) const {
;     ...
;         for (int ai = 0; ai < 2; ++ai)
; #pragma unroll
;             for (int m = 0; m < 4; ++m) { const int r = ai * HALF + wr * 64 + m * 16 + fr; const f32x2v sr = S[r]; const size_t off = (size_t)(u.pm * BM + r) * ldc + col0;
; #pragma unroll
;                 for (int bj = 0; bj < 2; ++bj)
; #pragma unroll
;                     for (int n = 0; n < 2; ++n) { const f32x4 bs = *(const f32x4*)(base + off + bj * HALF + n * 16); acc[ai][bj][m][n] = bs + cvv[bj][n] * (acc[ai][bj][m][n] * sr.y); }
;                 asm volatile("" : "+v"(acc[ai][0][m][0]), "+v"(acc[ai][0][m][1]), "+v"(acc[ai][1][m][0]), "+v"(acc[ai][1][m][1]));
;                 if (m & 1) asm volatile("" ::: "memory"); }
	v_pk_fma_f32 v[82:83], v[130:131], v[82:83], v[178:179]
	v_pk_fma_f32 v[84:85], v[132:133], v[84:85], v[180:181]
	v_add_u32_e32 v158, 0x80, v150
	global_load_dwordx4 v[164:167], v[188:189], off
	global_load_dwordx4 v[174:177], v[188:189], off offset:64
	global_load_dwordx4 v[178:181], v[188:189], off offset:512
	s_nop 0
	global_load_dwordx4 v[186:189], v[188:189], off offset:576
	ds_read_b64 v[160:161], v182 offset:8576
	v_ashrrev_i32_e32 v159, 31, v158
	v_lshlrev_b64 v[190:191], 12, v[158:159]
	v_lshl_add_u64 v[190:191], s[0:1], 0, v[190:191]
	v_lshl_add_u64 v[190:191], v[190:191], 0, v[168:169]
	s_waitcnt lgkmcnt(0)
	v_pk_mul_f32 v[80:81], v[80:81], v[160:161] op_sel:[0,1]
	v_pk_mul_f32 v[78:79], v[78:79], v[160:161] op_sel:[0,1]
	v_pk_mul_f32 v[76:77], v[76:77], v[160:161] op_sel:[0,1]
	v_pk_mul_f32 v[74:75], v[74:75], v[160:161] op_sel:[0,1]
	v_pk_mul_f32 v[72:73], v[72:73], v[160:161] op_sel:[0,1]
	v_pk_mul_f32 v[70:71], v[70:71], v[160:161] op_sel:[0,1]
	v_pk_mul_f32 v[68:69], v[68:69], v[160:161] op_sel:[0,1]
	v_pk_mul_f32 v[66:67], v[66:67], v[160:161] op_sel:[0,1]
	v_add_u32_e32 v160, 0x90, v150
	v_ashrrev_i32_e32 v161, 31, v160
	v_lshlrev_b64 v[192:193], 12, v[160:161]
	v_lshl_add_u64 v[192:193], s[0:1], 0, v[192:193]
	v_lshl_add_u64 v[192:193], v[192:193], 0, v[168:169]
	s_waitcnt vmcnt(3)
	v_pk_fma_f32 v[78:79], v[142:143], v[78:79], v[164:165]
	v_pk_fma_f32 v[80:81], v[144:145], v[80:81], v[166:167]
	s_waitcnt vmcnt(2)
	v_pk_fma_f32 v[74:75], v[138:139], v[74:75], v[174:175]
	v_pk_fma_f32 v[76:77], v[140:141], v[76:77], v[176:177]
	s_waitcnt vmcnt(1)
	v_pk_fma_f32 v[70:71], v[134:135], v[70:71], v[178:179]
	v_pk_fma_f32 v[72:73], v[136:137], v[72:73], v[180:181]
	s_waitcnt vmcnt(0)
	v_pk_fma_f32 v[66:67], v[130:131], v[66:67], v[186:187]
	v_pk_fma_f32 v[68:69], v[132:133], v[68:69], v[188:189]
	s_nop 0
	global_load_dwordx4 v[164:167], v[190:191], off
	global_load_dwordx4 v[174:177], v[190:191], off offset:64
	global_load_dwordx4 v[178:181], v[190:191], off offset:512
	global_load_dwordx4 v[186:189], v[190:191], off offset:576
	ds_read_b64 v[190:191], v182 offset:9216
	s_waitcnt lgkmcnt(0)
	v_pk_mul_f32 v[64:65], v[64:65], v[190:191] op_sel:[0,1]
	v_pk_mul_f32 v[62:63], v[62:63], v[190:191] op_sel:[0,1]
	v_pk_mul_f32 v[60:61], v[60:61], v[190:191] op_sel:[0,1]
	v_pk_mul_f32 v[58:59], v[58:59], v[190:191] op_sel:[0,1]
	v_pk_mul_f32 v[56:57], v[56:57], v[190:191] op_sel:[0,1]
	v_pk_mul_f32 v[54:55], v[54:55], v[190:191] op_sel:[0,1]
	v_pk_mul_f32 v[52:53], v[52:53], v[190:191] op_sel:[0,1]
	v_pk_mul_f32 v[50:51], v[50:51], v[190:191] op_sel:[0,1]
	s_waitcnt vmcnt(3)
	v_pk_fma_f32 v[62:63], v[142:143], v[62:63], v[164:165]
	v_pk_fma_f32 v[64:65], v[144:145], v[64:65], v[166:167]
	s_waitcnt vmcnt(2)
	v_pk_fma_f32 v[58:59], v[138:139], v[58:59], v[174:175]
	v_pk_fma_f32 v[60:61], v[140:141], v[60:61], v[176:177]
	s_waitcnt vmcnt(1)
	v_pk_fma_f32 v[54:55], v[134:135], v[54:55], v[178:179]
	v_pk_fma_f32 v[56:57], v[136:137], v[56:57], v[180:181]
	s_waitcnt vmcnt(0)
	v_pk_fma_f32 v[50:51], v[130:131], v[50:51], v[186:187]
	v_pk_fma_f32 v[52:53], v[132:133], v[52:53], v[188:189]
	v_add_u32_e32 v164, 0xa0, v150
	global_load_dwordx4 v[174:177], v[192:193], off
	global_load_dwordx4 v[178:181], v[192:193], off offset:64
	global_load_dwordx4 v[186:189], v[192:193], off offset:512
	s_nop 0
	global_load_dwordx4 v[190:193], v[192:193], off offset:576
	ds_read_b64 v[166:167], v182 offset:9344
	v_ashrrev_i32_e32 v165, 31, v164
	v_lshlrev_b64 v[194:195], 12, v[164:165]
	v_lshl_add_u64 v[194:195], s[0:1], 0, v[194:195]
	v_lshl_add_u64 v[194:195], v[194:195], 0, v[168:169]
	s_waitcnt lgkmcnt(0)
	v_pk_mul_f32 v[48:49], v[48:49], v[166:167] op_sel:[0,1]
	v_pk_mul_f32 v[46:47], v[46:47], v[166:167] op_sel:[0,1]
	v_pk_mul_f32 v[44:45], v[44:45], v[166:167] op_sel:[0,1]
	v_pk_mul_f32 v[42:43], v[42:43], v[166:167] op_sel:[0,1]
	v_pk_mul_f32 v[40:41], v[40:41], v[166:167] op_sel:[0,1]
	v_pk_mul_f32 v[38:39], v[38:39], v[166:167] op_sel:[0,1]
	v_pk_mul_f32 v[36:37], v[36:37], v[166:167] op_sel:[0,1]
	v_pk_mul_f32 v[34:35], v[34:35], v[166:167] op_sel:[0,1]
	v_add_u32_e32 v166, 0xb0, v150
	v_ashrrev_i32_e32 v167, 31, v166
	s_waitcnt vmcnt(3)
	v_pk_fma_f32 v[46:47], v[142:143], v[46:47], v[174:175]
	v_pk_fma_f32 v[48:49], v[144:145], v[48:49], v[176:177]
	s_waitcnt vmcnt(2)
	v_pk_fma_f32 v[42:43], v[138:139], v[42:43], v[178:179]
	v_pk_fma_f32 v[44:45], v[140:141], v[44:45], v[180:181]
	s_waitcnt vmcnt(1)
	v_pk_fma_f32 v[38:39], v[134:135], v[38:39], v[186:187]
	v_pk_fma_f32 v[40:41], v[136:137], v[40:41], v[188:189]
	s_waitcnt vmcnt(0)
	v_pk_fma_f32 v[34:35], v[130:131], v[34:35], v[190:191]
	v_pk_fma_f32 v[36:37], v[132:133], v[36:37], v[192:193]
	s_nop 0
	global_load_dwordx4 v[174:177], v[194:195], off
	global_load_dwordx4 v[178:181], v[194:195], off offset:64
	global_load_dwordx4 v[186:189], v[194:195], off offset:512
	global_load_dwordx4 v[190:193], v[194:195], off offset:576
	ds_read_b64 v[204:205], v182 offset:9472
	v_lshlrev_b64 v[194:195], 12, v[166:167]
	v_lshl_add_u64 v[194:195], s[0:1], 0, v[194:195]
	v_lshl_add_u64 v[168:169], v[194:195], 0, v[168:169]
	v_mov_b32_e32 v194, v115
	s_waitcnt lgkmcnt(0)
	v_pk_mul_f32 v[32:33], v[32:33], v[204:205] op_sel:[0,1]
	v_pk_mul_f32 v[30:31], v[30:31], v[204:205] op_sel:[0,1]
	v_pk_mul_f32 v[28:29], v[28:29], v[204:205] op_sel:[0,1]
	v_pk_mul_f32 v[26:27], v[26:27], v[204:205] op_sel:[0,1]
	v_pk_mul_f32 v[24:25], v[24:25], v[204:205] op_sel:[0,1]
	v_pk_mul_f32 v[22:23], v[22:23], v[204:205] op_sel:[0,1]
	v_pk_mul_f32 v[20:21], v[20:21], v[204:205] op_sel:[0,1]
	v_pk_mul_f32 v[18:19], v[18:19], v[204:205] op_sel:[0,1]
	v_mov_b32_e32 v195, v116
	s_waitcnt vmcnt(3)
;     __device__ __forceinline__ bool run(const f32x4 (&v)[2][2][4][2], const Unit& u, int wr, int wc, int fr, int fq, PG8_LAS unsigned char* lds, int wid, int lane) const {
;     ...
;                 float s = 0.f;
; #pragma unroll
;                 for (int bj = 0; bj < 2; ++bj)
; #pragma unroll
;                     for (int n = 0; n < 2; ++n) { const f32x4 x = v[ai][bj][m][n]; s += (x[0] + x[1]) + (x[2] + x[3]); }
;                 s += __shfl_xor(s, 16); s += __shfl_xor(s, 32);
;                 const float mw = s * (1.0f / 64.0f); float q = 0.f;
; #pragma unroll
;                 for (int bj = 0; bj < 2; ++bj)
; #pragma unroll
;                     for (int n = 0; n < 2; ++n) { const f32x4 d = v[ai][bj][m][n] - mw; q += (d[0] * d[0] + d[1] * d[1]) + (d[2] * d[2] + d[3] * d[3]); }
;                 q += __shfl_xor(q, 16); q += __shfl_xor(q, 32);
;                 if (fq == 0) P[(ai * HALF + wr * 64 + m * 16 + fr) * 4 + wc] = (f32x2v){mw, q};
;     __device__ __forceinline__ void fused(f32x4 (&acc)[2][2][4][2], const Unit& u, int wr, int wc, int fr, int fq, PG8_LAS unsigned char* lds, int wid, int lane) const {
;     ...
;         for (int ai = 0; ai < 2; ++ai)
; #pragma unroll
;             for (int m = 0; m < 4; ++m) { const int r = ai * HALF + wr * 64 + m * 16 + fr; const f32x2v sr = S[r]; const size_t off = (size_t)(u.pm * BM + r) * ldc + col0;
; #pragma unroll
;                 for (int bj = 0; bj < 2; ++bj)
; #pragma unroll
;                     for (int n = 0; n < 2; ++n) { const f32x4 bs = *(const f32x4*)(base + off + bj * HALF + n * 16); acc[ai][bj][m][n] = bs + cvv[bj][n] * (acc[ai][bj][m][n] * sr.y); }
;                 asm volatile("" : "+v"(acc[ai][0][m][0]), "+v"(acc[ai][0][m][1]), "+v"(acc[ai][1][m][0]), "+v"(acc[ai][1][m][1]));
;                 if (m & 1) asm volatile("" ::: "memory"); }
	v_pk_fma_f32 v[30:31], v[142:143], v[30:31], v[174:175]
	v_pk_fma_f32 v[32:33], v[144:145], v[32:33], v[176:177]
	s_waitcnt vmcnt(2)
	v_pk_fma_f32 v[26:27], v[138:139], v[26:27], v[178:179]
	v_pk_fma_f32 v[28:29], v[140:141], v[28:29], v[180:181]
	s_waitcnt vmcnt(1)
	v_pk_fma_f32 v[22:23], v[134:135], v[22:23], v[186:187]
	v_pk_fma_f32 v[24:25], v[136:137], v[24:25], v[188:189]
	s_waitcnt vmcnt(0)
	v_pk_fma_f32 v[18:19], v[130:131], v[18:19], v[190:191]
	v_pk_fma_f32 v[20:21], v[132:133], v[20:21], v[192:193]
	v_pk_add_f32 v[174:175], v[194:195], v[196:197]
	global_load_dwordx4 v[176:179], v[168:169], off
	global_load_dwordx4 v[186:189], v[168:169], off offset:64
	global_load_dwordx4 v[190:193], v[168:169], off offset:512
	global_load_dwordx4 v[194:197], v[168:169], off offset:576
	v_pk_add_f32 v[180:181], v[198:199], v[200:201]
	v_add_f32_e32 v174, v174, v175
	v_pk_add_f32 v[168:169], v[180:181], v[180:181] op_sel_hi:[0,1]
	v_add_f32_e32 v209, 0, v174
	v_mov_b32_e32 v168, v128
	v_pk_add_f32 v[198:199], v[202:203], v[206:207]
	v_pk_add_f32 v[168:169], v[168:169], v[208:209]
	s_nop 0
	v_pk_add_f32 v[168:169], v[198:199], v[168:169]
	s_nop 0
	v_add_f32_e32 v168, v168, v169
	v_mov_b32_e32 v169, v168
	s_nop 1
	v_permlane16_swap_b32 v168, v169
	s_waitcnt lgkmcnt(0)
	v_add_f32_e32 v168, v168, v169
	v_mov_b32_e32 v169, v168
	s_nop 1
	v_permlane32_swap_b32 v168, v169
	s_waitcnt lgkmcnt(0)
	v_add_f32_e32 v168, v168, v169
	v_fmamk_f32 v174, v168, 0xbc800000, v117
	v_fmamk_f32 v180, v168, 0xbc800000, v115
	v_fmamk_f32 v185, v168, 0xbc800000, v121
	v_fmamk_f32 v199, v168, 0xbc800000, v119
	v_fmamk_f32 v169, v168, 0xbc800000, v116
	v_fmamk_f32 v175, v168, 0xbc800000, v114
	v_fmamk_f32 v181, v168, 0xbc800000, v120
	v_fmamk_f32 v198, v168, 0xbc800000, v118
	v_fmamk_f32 v201, v168, 0xbc800000, v125
	v_fmamk_f32 v203, v168, 0xbc800000, v123
	v_mul_f32_e32 v180, v180, v180
	v_mul_f32_e32 v174, v174, v174
	v_mul_f32_e32 v199, v199, v199
	v_mul_f32_e32 v185, v185, v185
	v_fmamk_f32 v200, v168, 0xbc800000, v124
	v_fmamk_f32 v202, v168, 0xbc800000, v122
	v_fmamk_f32 v205, v168, 0xbc800000, v129
	v_fmamk_f32 v207, v168, 0xbc800000, v127
	v_mul_f32_e32 v203, v203, v203
	v_mul_f32_e32 v201, v201, v201
	v_fmac_f32_e32 v180, v175, v175
	v_fmac_f32_e32 v174, v169, v169
	v_fmac_f32_e32 v199, v198, v198
	v_fmac_f32_e32 v185, v181, v181
	v_fmamk_f32 v204, v168, 0xbc800000, v128
	v_fmamk_f32 v206, v168, 0xbc800000, v126
	v_mul_f32_e32 v207, v207, v207
	v_mul_f32_e32 v205, v205, v205
	v_fmac_f32_e32 v203, v202, v202
	v_fmac_f32_e32 v201, v200, v200
	v_add_f32_e32 v169, v180, v174
	v_add_f32_e32 v174, v199, v185
	v_fmac_f32_e32 v207, v206, v206
	v_fmac_f32_e32 v205, v204, v204
	v_add_f32_e32 v175, v203, v201
	v_add_f32_e32 v169, v169, v174
	v_add_f32_e32 v180, v207, v205
	v_add_f32_e32 v169, v175, v169
	v_add_f32_e32 v169, v180, v169
	ds_bpermute_b32 v174, v171, v169
	ds_read_b64 v[180:181], v182 offset:9600
	s_waitcnt lgkmcnt(1)
	v_add_f32_e32 v169, v169, v174
	ds_bpermute_b32 v174, v172, v169
	s_waitcnt lgkmcnt(1)
	v_pk_mul_f32 v[16:17], v[16:17], v[180:181] op_sel:[0,1]
	v_pk_mul_f32 v[14:15], v[14:15], v[180:181] op_sel:[0,1]
	v_pk_mul_f32 v[12:13], v[12:13], v[180:181] op_sel:[0,1]
	v_pk_mul_f32 v[10:11], v[10:11], v[180:181] op_sel:[0,1]
	v_pk_mul_f32 v[8:9], v[8:9], v[180:181] op_sel:[0,1]
	v_pk_mul_f32 v[6:7], v[6:7], v[180:181] op_sel:[0,1]
	v_pk_mul_f32 v[4:5], v[4:5], v[180:181] op_sel:[0,1]
	v_pk_mul_f32 v[2:3], v[2:3], v[180:181] op_sel:[0,1]
	s_waitcnt vmcnt(3)
	v_pk_fma_f32 v[14:15], v[142:143], v[14:15], v[176:177]
	v_pk_fma_f32 v[16:17], v[144:145], v[16:17], v[178:179]
	s_waitcnt vmcnt(2)
	v_pk_fma_f32 v[10:11], v[138:139], v[10:11], v[186:187]
	v_pk_fma_f32 v[12:13], v[140:141], v[12:13], v[188:189]
	s_waitcnt vmcnt(1)
	v_pk_fma_f32 v[6:7], v[134:135], v[6:7], v[190:191]
	v_pk_fma_f32 v[8:9], v[136:137], v[8:9], v[192:193]
	s_waitcnt vmcnt(0)
	v_pk_fma_f32 v[2:3], v[130:131], v[2:3], v[194:195]
	v_pk_fma_f32 v[4:5], v[132:133], v[4:5], v[196:197]
	s_nop 0
	s_and_saveexec_b64 s[0:1], s[4:5]
	s_cbranch_execz .LBB0_1075
	s_lshl_b32 s3, s52, 11
	s_add_i32 s3, s29, s3
	v_mul_f32_e32 v130, 0x3c800000, v168
	v_lshl_add_u32 v132, v170, 5, s3
	s_waitcnt lgkmcnt(0)
	v_add_f32_e32 v131, v169, v174
	ds_write_b64 v132, v[130:131]
;     __device__ __forceinline__ bool run(const f32x4 (&v)[2][2][4][2], const Unit& u, int wr, int wc, int fr, int fq, PG8_LAS unsigned char* lds, int wid, int lane) const {
;     ...
;             for (int m = 0; m < 4; ++m) {
;                 float s = 0.f;
; #pragma unroll
;                 for (int bj = 0; bj < 2; ++bj)
; #pragma unroll
;                     for (int n = 0; n < 2; ++n) { const f32x4 x = v[ai][bj][m][n]; s += (x[0] + x[1]) + (x[2] + x[3]); }
;                 s += __shfl_xor(s, 16); s += __shfl_xor(s, 32);
;                 const float mw = s * (1.0f / 64.0f); float q = 0.f;
; #pragma unroll
;                 for (int bj = 0; bj < 2; ++bj)
; #pragma unroll
;                     for (int n = 0; n < 2; ++n) { const f32x4 d = v[ai][bj][m][n] - mw; q += (d[0] * d[0] + d[1] * d[1]) + (d[2] * d[2] + d[3] * d[3]); }
;                 q += __shfl_xor(q, 16); q += __shfl_xor(q, 32);
;                 if (fq == 0) P[(ai * HALF + wr * 64 + m * 16 + fr) * 4 + wc] = (f32x2v){mw, q};
.LBB0_1075:
	s_or_b64 exec, exec, s[0:1]
	v_mov_b32_e32 v130, v111
	v_mov_b32_e32 v131, v112
	v_mov_b32_e32 v132, v110
	v_mov_b32_e32 v133, v113
	v_pk_add_f32 v[130:131], v[130:131], v[132:133]
	v_mov_b32_e32 v132, v107
	v_mov_b32_e32 v133, v108
	v_mov_b32_e32 v134, v106
	v_mov_b32_e32 v135, v109
	v_pk_add_f32 v[132:133], v[132:133], v[134:135]
	v_add_f32_e32 v130, v130, v131
	v_pk_add_f32 v[132:133], v[132:133], v[132:133] op_sel_hi:[0,1]
	v_add_f32_e32 v131, 0, v130
	v_add_f32_e32 v135, v102, v103
	v_add_f32_e32 v137, v104, v105
	v_mov_b32_e32 v134, v98
	v_mov_b32_e32 v136, v99
	v_mov_b32_e32 v132, v100
	v_mov_b32_e32 v130, v101
	v_pk_add_f32 v[134:135], v[134:135], v[136:137]
	v_pk_add_f32 v[130:131], v[132:133], v[130:131]
	s_nop 0
	v_pk_add_f32 v[130:131], v[134:135], v[130:131]
	s_nop 0
	v_add_f32_e32 v130, v130, v131
	v_mov_b32_e32 v131, v130
	s_nop 1
	v_permlane16_swap_b32 v130, v131
	s_waitcnt lgkmcnt(0)
	v_add_f32_e32 v130, v130, v131
	v_mov_b32_e32 v131, v130
	s_nop 1
	v_permlane32_swap_b32 v130, v131
	s_waitcnt lgkmcnt(0)
	v_add_f32_e32 v130, v130, v131
	v_fmamk_f32 v132, v130, 0xbc800000, v113
	v_fmamk_f32 v134, v130, 0xbc800000, v111
	v_fmamk_f32 v131, v130, 0xbc800000, v112
	v_fmamk_f32 v133, v130, 0xbc800000, v110
	v_mul_f32_e32 v134, v134, v134
	v_mul_f32_e32 v132, v132, v132
	v_fmac_f32_e32 v134, v133, v133
	v_fmac_f32_e32 v132, v131, v131
	v_fmamk_f32 v133, v130, 0xbc800000, v109
	v_fmamk_f32 v135, v130, 0xbc800000, v107
	v_add_f32_e32 v131, v134, v132
	v_fmamk_f32 v132, v130, 0xbc800000, v108
	v_fmamk_f32 v134, v130, 0xbc800000, v106
	v_mul_f32_e32 v135, v135, v135
	v_mul_f32_e32 v133, v133, v133
	v_fmac_f32_e32 v135, v134, v134
	v_fmac_f32_e32 v133, v132, v132
	v_add_f32_e32 v132, v135, v133
	v_fmamk_f32 v133, v130, 0xbc800000, v105
	v_fmamk_f32 v135, v130, 0xbc800000, v103
	v_add_f32_e32 v131, v131, v132
	v_fmamk_f32 v132, v130, 0xbc800000, v104
	v_fmamk_f32 v134, v130, 0xbc800000, v102
	v_mul_f32_e32 v135, v135, v135
	v_mul_f32_e32 v133, v133, v133
	v_fmac_f32_e32 v135, v134, v134
	v_fmac_f32_e32 v133, v132, v132
	v_add_f32_e32 v132, v135, v133
	v_fmamk_f32 v133, v130, 0xbc800000, v101
	v_fmamk_f32 v135, v130, 0xbc800000, v99
	v_add_f32_e32 v131, v132, v131
	v_fmamk_f32 v132, v130, 0xbc800000, v100
	v_fmamk_f32 v134, v130, 0xbc800000, v98
	v_mul_f32_e32 v135, v135, v135
	v_mul_f32_e32 v133, v133, v133
	v_fmac_f32_e32 v135, v134, v134
	v_fmac_f32_e32 v133, v132, v132
	v_add_f32_e32 v132, v135, v133
	v_add_f32_e32 v131, v132, v131
	v_mov_b32_e32 v132, v131
	s_nop 1
	v_permlane16_swap_b32 v131, v132
	s_waitcnt lgkmcnt(0)
	v_add_f32_e32 v131, v131, v132
	ds_bpermute_b32 v132, v172, v131
	s_and_saveexec_b64 s[0:1], s[4:5]
	s_cbranch_execz .LBB0_1077
	s_lshl_b32 s3, s52, 11
	s_add_i32 s3, s29, s3
	v_mul_f32_e32 v130, 0x3c800000, v130
	v_lshl_add_u32 v133, v170, 5, s3
	s_waitcnt lgkmcnt(0)
	v_add_f32_e32 v131, v131, v132
	ds_write_b64 v133, v[130:131] offset:512
.LBB0_1077:
	s_or_b64 exec, exec, s[0:1]
	v_mov_b32_e32 v130, v95
	v_mov_b32_e32 v131, v96
	s_waitcnt lgkmcnt(0)
	v_mov_b32_e32 v132, v94
	v_mov_b32_e32 v133, v97
	v_pk_add_f32 v[130:131], v[130:131], v[132:133]
	v_mov_b32_e32 v132, v91
	v_mov_b32_e32 v133, v92
	v_mov_b32_e32 v134, v90
	v_mov_b32_e32 v135, v93
	v_pk_add_f32 v[132:133], v[132:133], v[134:135]
	v_add_f32_e32 v130, v130, v131
	v_pk_add_f32 v[132:133], v[132:133], v[132:133] op_sel_hi:[0,1]
	v_add_f32_e32 v131, 0, v130
	v_add_f32_e32 v135, v86, v87
	v_add_f32_e32 v137, v88, v89
	v_mov_b32_e32 v134, v82
	v_mov_b32_e32 v136, v83
	v_mov_b32_e32 v132, v84
	v_mov_b32_e32 v130, v85
	v_pk_add_f32 v[134:135], v[134:135], v[136:137]
	v_pk_add_f32 v[130:131], v[132:133], v[130:131]
	s_nop 0
	v_pk_add_f32 v[130:131], v[134:135], v[130:131]
	s_nop 0
	v_add_f32_e32 v130, v130, v131
	v_mov_b32_e32 v131, v130
	s_nop 1
	v_permlane16_swap_b32 v130, v131
	s_waitcnt lgkmcnt(0)
	v_add_f32_e32 v130, v130, v131
	v_mov_b32_e32 v131, v130
	s_nop 1
	v_permlane32_swap_b32 v130, v131
	s_waitcnt lgkmcnt(0)
	v_add_f32_e32 v130, v130, v131
	v_fmamk_f32 v132, v130, 0xbc800000, v97
	v_fmamk_f32 v134, v130, 0xbc800000, v95
	v_fmamk_f32 v131, v130, 0xbc800000, v96
	v_fmamk_f32 v133, v130, 0xbc800000, v94
	v_mul_f32_e32 v134, v134, v134
	v_mul_f32_e32 v132, v132, v132
	v_fmac_f32_e32 v134, v133, v133
	v_fmac_f32_e32 v132, v131, v131
	v_fmamk_f32 v133, v130, 0xbc800000, v93
	v_fmamk_f32 v135, v130, 0xbc800000, v91
	v_add_f32_e32 v131, v134, v132
	v_fmamk_f32 v132, v130, 0xbc800000, v92
	v_fmamk_f32 v134, v130, 0xbc800000, v90
	v_mul_f32_e32 v135, v135, v135
	v_mul_f32_e32 v133, v133, v133
	v_fmac_f32_e32 v135, v134, v134
	v_fmac_f32_e32 v133, v132, v132
	v_add_f32_e32 v132, v135, v133
	v_fmamk_f32 v133, v130, 0xbc800000, v89
	v_fmamk_f32 v135, v130, 0xbc800000, v87
	v_add_f32_e32 v131, v131, v132
	v_fmamk_f32 v132, v130, 0xbc800000, v88
	v_fmamk_f32 v134, v130, 0xbc800000, v86
	v_mul_f32_e32 v135, v135, v135
	v_mul_f32_e32 v133, v133, v133
	v_fmac_f32_e32 v135, v134, v134
	v_fmac_f32_e32 v133, v132, v132
	v_add_f32_e32 v132, v135, v133
	v_fmamk_f32 v133, v130, 0xbc800000, v85
	v_fmamk_f32 v135, v130, 0xbc800000, v83
	v_add_f32_e32 v131, v132, v131
	v_fmamk_f32 v132, v130, 0xbc800000, v84
	v_fmamk_f32 v134, v130, 0xbc800000, v82
	v_mul_f32_e32 v135, v135, v135
	v_mul_f32_e32 v133, v133, v133
	v_fmac_f32_e32 v135, v134, v134
	v_fmac_f32_e32 v133, v132, v132
	v_add_f32_e32 v132, v135, v133
	v_add_f32_e32 v131, v132, v131
	v_mov_b32_e32 v132, v131
	s_nop 1
	v_permlane16_swap_b32 v131, v132
	s_waitcnt lgkmcnt(0)
	v_add_f32_e32 v131, v131, v132
	ds_bpermute_b32 v132, v172, v131
	s_and_saveexec_b64 s[0:1], s[4:5]
	s_cbranch_execz .LBB0_1079
	s_lshl_b32 s3, s52, 11
	s_add_i32 s3, s29, s3
	v_mul_f32_e32 v130, 0x3c800000, v130
	v_lshl_add_u32 v133, v170, 5, s3
	s_waitcnt lgkmcnt(0)
	v_add_f32_e32 v131, v131, v132
	ds_write_b64 v133, v[130:131] offset:1024
;     __device__ __forceinline__ bool run(const f32x4 (&v)[2][2][4][2], const Unit& u, int wr, int wc, int fr, int fq, PG8_LAS unsigned char* lds, int wid, int lane) const {
;     ...
;             for (int m = 0; m < 4; ++m) {
;                 float s = 0.f;
; #pragma unroll
;                 for (int bj = 0; bj < 2; ++bj)
; #pragma unroll
;                     for (int n = 0; n < 2; ++n) { const f32x4 x = v[ai][bj][m][n]; s += (x[0] + x[1]) + (x[2] + x[3]); }
;                 s += __shfl_xor(s, 16); s += __shfl_xor(s, 32);
;                 const float mw = s * (1.0f / 64.0f); float q = 0.f;
; #pragma unroll
;                 for (int bj = 0; bj < 2; ++bj)
; #pragma unroll
;                     for (int n = 0; n < 2; ++n) { const f32x4 d = v[ai][bj][m][n] - mw; q += (d[0] * d[0] + d[1] * d[1]) + (d[2] * d[2] + d[3] * d[3]); }
;                 q += __shfl_xor(q, 16); q += __shfl_xor(q, 32);
;                 if (fq == 0) P[(ai * HALF + wr * 64 + m * 16 + fr) * 4 + wc] = (f32x2v){mw, q};
.LBB0_1079:
	s_or_b64 exec, exec, s[0:1]
	v_mov_b32_e32 v130, v79
	v_mov_b32_e32 v131, v80
	s_waitcnt lgkmcnt(0)
	v_mov_b32_e32 v132, v78
	v_mov_b32_e32 v133, v81
	v_pk_add_f32 v[130:131], v[130:131], v[132:133]
	v_mov_b32_e32 v132, v75
	v_mov_b32_e32 v133, v76
	v_mov_b32_e32 v134, v74
	v_mov_b32_e32 v135, v77
	v_pk_add_f32 v[132:133], v[132:133], v[134:135]
	v_add_f32_e32 v130, v130, v131
	v_pk_add_f32 v[132:133], v[132:133], v[132:133] op_sel_hi:[0,1]
	v_add_f32_e32 v131, 0, v130
	v_add_f32_e32 v135, v70, v71
	v_add_f32_e32 v137, v72, v73
	v_mov_b32_e32 v134, v66
	v_mov_b32_e32 v136, v67
	v_mov_b32_e32 v132, v68
	v_mov_b32_e32 v130, v69
	v_pk_add_f32 v[134:135], v[134:135], v[136:137]
	v_pk_add_f32 v[130:131], v[132:133], v[130:131]
	s_nop 0
	v_pk_add_f32 v[130:131], v[134:135], v[130:131]
	s_nop 0
	v_add_f32_e32 v130, v130, v131
	v_mov_b32_e32 v131, v130
	s_nop 1
	v_permlane16_swap_b32 v130, v131
	s_waitcnt lgkmcnt(0)
	v_add_f32_e32 v130, v130, v131
	v_mov_b32_e32 v131, v130
	s_nop 1
	v_permlane32_swap_b32 v130, v131
	s_waitcnt lgkmcnt(0)
	v_add_f32_e32 v130, v130, v131
	v_fmamk_f32 v132, v130, 0xbc800000, v81
	v_fmamk_f32 v134, v130, 0xbc800000, v79
	v_fmamk_f32 v131, v130, 0xbc800000, v80
	v_fmamk_f32 v133, v130, 0xbc800000, v78
	v_mul_f32_e32 v134, v134, v134
	v_mul_f32_e32 v132, v132, v132
	v_fmac_f32_e32 v134, v133, v133
	v_fmac_f32_e32 v132, v131, v131
	v_fmamk_f32 v133, v130, 0xbc800000, v77
	v_fmamk_f32 v135, v130, 0xbc800000, v75
	v_add_f32_e32 v131, v134, v132
	v_fmamk_f32 v132, v130, 0xbc800000, v76
	v_fmamk_f32 v134, v130, 0xbc800000, v74
	v_mul_f32_e32 v135, v135, v135
	v_mul_f32_e32 v133, v133, v133
	v_fmac_f32_e32 v135, v134, v134
	v_fmac_f32_e32 v133, v132, v132
	v_add_f32_e32 v132, v135, v133
	v_fmamk_f32 v133, v130, 0xbc800000, v73
	v_fmamk_f32 v135, v130, 0xbc800000, v71
	v_add_f32_e32 v131, v131, v132
	v_fmamk_f32 v132, v130, 0xbc800000, v72
	v_fmamk_f32 v134, v130, 0xbc800000, v70
	v_mul_f32_e32 v135, v135, v135
	v_mul_f32_e32 v133, v133, v133
	v_fmac_f32_e32 v135, v134, v134
	v_fmac_f32_e32 v133, v132, v132
	v_add_f32_e32 v132, v135, v133
	v_fmamk_f32 v133, v130, 0xbc800000, v69
	v_fmamk_f32 v135, v130, 0xbc800000, v67
	v_add_f32_e32 v131, v132, v131
	v_fmamk_f32 v132, v130, 0xbc800000, v68
	v_fmamk_f32 v134, v130, 0xbc800000, v66
	v_mul_f32_e32 v135, v135, v135
	v_mul_f32_e32 v133, v133, v133
	v_fmac_f32_e32 v135, v134, v134
	v_fmac_f32_e32 v133, v132, v132
	v_add_f32_e32 v132, v135, v133
	v_add_f32_e32 v131, v132, v131
	v_mov_b32_e32 v132, v131
	s_nop 1
	v_permlane16_swap_b32 v131, v132
	s_waitcnt lgkmcnt(0)
	v_add_f32_e32 v131, v131, v132
	ds_bpermute_b32 v132, v172, v131
	s_and_saveexec_b64 s[0:1], s[4:5]
	s_cbranch_execz .LBB0_1081
	s_lshl_b32 s3, s52, 11
	s_add_i32 s3, s29, s3
	v_mul_f32_e32 v130, 0x3c800000, v130
	v_lshl_add_u32 v133, v170, 5, s3
	s_waitcnt lgkmcnt(0)
	v_add_f32_e32 v131, v131, v132
	ds_write_b64 v133, v[130:131] offset:1536
.LBB0_1081:
	s_or_b64 exec, exec, s[0:1]
	v_mov_b32_e32 v130, v63
	v_mov_b32_e32 v131, v64
	s_waitcnt lgkmcnt(0)
	v_mov_b32_e32 v132, v62
	v_mov_b32_e32 v133, v65
	v_pk_add_f32 v[130:131], v[130:131], v[132:133]
	v_mov_b32_e32 v132, v59
	v_mov_b32_e32 v133, v60
	v_mov_b32_e32 v134, v58
	v_mov_b32_e32 v135, v61
	v_pk_add_f32 v[132:133], v[132:133], v[134:135]
	v_add_f32_e32 v130, v130, v131
	v_pk_add_f32 v[132:133], v[132:133], v[132:133] op_sel_hi:[0,1]
	v_add_f32_e32 v131, 0, v130
	v_add_f32_e32 v135, v54, v55
	v_add_f32_e32 v137, v56, v57
	v_mov_b32_e32 v134, v50
	v_mov_b32_e32 v136, v51
	v_mov_b32_e32 v132, v52
	v_mov_b32_e32 v130, v53
	v_pk_add_f32 v[134:135], v[134:135], v[136:137]
	v_pk_add_f32 v[130:131], v[132:133], v[130:131]
	s_nop 0
	v_pk_add_f32 v[130:131], v[134:135], v[130:131]
	s_nop 0
	v_add_f32_e32 v130, v130, v131
	v_mov_b32_e32 v131, v130
	s_nop 1
	v_permlane16_swap_b32 v130, v131
	s_waitcnt lgkmcnt(0)
	v_add_f32_e32 v130, v130, v131
	v_mov_b32_e32 v131, v130
	s_nop 1
	v_permlane32_swap_b32 v130, v131
	s_waitcnt lgkmcnt(0)
	v_add_f32_e32 v130, v130, v131
	v_fmamk_f32 v132, v130, 0xbc800000, v65
	v_fmamk_f32 v134, v130, 0xbc800000, v63
	v_fmamk_f32 v131, v130, 0xbc800000, v64
	v_fmamk_f32 v133, v130, 0xbc800000, v62
	v_mul_f32_e32 v134, v134, v134
	v_mul_f32_e32 v132, v132, v132
	v_fmac_f32_e32 v134, v133, v133
	v_fmac_f32_e32 v132, v131, v131
	v_fmamk_f32 v133, v130, 0xbc800000, v61
	v_fmamk_f32 v135, v130, 0xbc800000, v59
	v_add_f32_e32 v131, v134, v132
	v_fmamk_f32 v132, v130, 0xbc800000, v60
	v_fmamk_f32 v134, v130, 0xbc800000, v58
	v_mul_f32_e32 v135, v135, v135
	v_mul_f32_e32 v133, v133, v133
	v_fmac_f32_e32 v135, v134, v134
	v_fmac_f32_e32 v133, v132, v132
	v_add_f32_e32 v132, v135, v133
	v_fmamk_f32 v133, v130, 0xbc800000, v57
	v_fmamk_f32 v135, v130, 0xbc800000, v55
	v_add_f32_e32 v131, v131, v132
	v_fmamk_f32 v132, v130, 0xbc800000, v56
	v_fmamk_f32 v134, v130, 0xbc800000, v54
	v_mul_f32_e32 v135, v135, v135
	v_mul_f32_e32 v133, v133, v133
	v_fmac_f32_e32 v135, v134, v134
	v_fmac_f32_e32 v133, v132, v132
	v_add_f32_e32 v132, v135, v133
	v_fmamk_f32 v133, v130, 0xbc800000, v53
	v_fmamk_f32 v135, v130, 0xbc800000, v51
	v_add_f32_e32 v131, v132, v131
	v_fmamk_f32 v132, v130, 0xbc800000, v52
	v_fmamk_f32 v134, v130, 0xbc800000, v50
	v_mul_f32_e32 v135, v135, v135
	v_mul_f32_e32 v133, v133, v133
	v_fmac_f32_e32 v135, v134, v134
	v_fmac_f32_e32 v133, v132, v132
	v_add_f32_e32 v132, v135, v133
	v_add_f32_e32 v131, v132, v131
	v_mov_b32_e32 v132, v131
	s_nop 1
	v_permlane16_swap_b32 v131, v132
	s_waitcnt lgkmcnt(0)
	v_add_f32_e32 v131, v131, v132
	ds_bpermute_b32 v132, v172, v131
	s_and_saveexec_b64 s[0:1], s[4:5]
	s_cbranch_execz .LBB0_1083
	s_lshl_b32 s3, s52, 11
	s_add_i32 s3, s29, s3
	v_mul_f32_e32 v130, 0x3c800000, v130
	v_lshl_add_u32 v133, v170, 5, s3
	s_waitcnt lgkmcnt(0)
	v_add_f32_e32 v131, v131, v132
	ds_write_b64 v133, v[130:131] offset:4096
;     __device__ __forceinline__ bool run(const f32x4 (&v)[2][2][4][2], const Unit& u, int wr, int wc, int fr, int fq, PG8_LAS unsigned char* lds, int wid, int lane) const {
;     ...
;             for (int m = 0; m < 4; ++m) {
;                 float s = 0.f;
; #pragma unroll
;                 for (int bj = 0; bj < 2; ++bj)
; #pragma unroll
;                     for (int n = 0; n < 2; ++n) { const f32x4 x = v[ai][bj][m][n]; s += (x[0] + x[1]) + (x[2] + x[3]); }
;                 s += __shfl_xor(s, 16); s += __shfl_xor(s, 32);
;                 const float mw = s * (1.0f / 64.0f); float q = 0.f;
; #pragma unroll
;                 for (int bj = 0; bj < 2; ++bj)
; #pragma unroll
;                     for (int n = 0; n < 2; ++n) { const f32x4 d = v[ai][bj][m][n] - mw; q += (d[0] * d[0] + d[1] * d[1]) + (d[2] * d[2] + d[3] * d[3]); }
;                 q += __shfl_xor(q, 16); q += __shfl_xor(q, 32);
;                 if (fq == 0) P[(ai * HALF + wr * 64 + m * 16 + fr) * 4 + wc] = (f32x2v){mw, q};
.LBB0_1083:
	s_or_b64 exec, exec, s[0:1]
	v_mov_b32_e32 v130, v47
	v_mov_b32_e32 v131, v48
	s_waitcnt lgkmcnt(0)
	v_mov_b32_e32 v132, v46
	v_mov_b32_e32 v133, v49
	v_pk_add_f32 v[130:131], v[130:131], v[132:133]
	v_mov_b32_e32 v132, v43
	v_mov_b32_e32 v133, v44
	v_mov_b32_e32 v134, v42
	v_mov_b32_e32 v135, v45
	v_pk_add_f32 v[132:133], v[132:133], v[134:135]
	v_add_f32_e32 v130, v130, v131
	v_pk_add_f32 v[132:133], v[132:133], v[132:133] op_sel_hi:[0,1]
	v_add_f32_e32 v131, 0, v130
	v_add_f32_e32 v135, v38, v39
	v_add_f32_e32 v137, v40, v41
	v_mov_b32_e32 v134, v34
	v_mov_b32_e32 v136, v35
	v_mov_b32_e32 v132, v36
	v_mov_b32_e32 v130, v37
	v_pk_add_f32 v[134:135], v[134:135], v[136:137]
	v_pk_add_f32 v[130:131], v[132:133], v[130:131]
	s_nop 0
	v_pk_add_f32 v[130:131], v[134:135], v[130:131]
	s_nop 0
	v_add_f32_e32 v130, v130, v131
	v_mov_b32_e32 v131, v130
	s_nop 1
	v_permlane16_swap_b32 v130, v131
	s_waitcnt lgkmcnt(0)
	v_add_f32_e32 v130, v130, v131
	v_mov_b32_e32 v131, v130
	s_nop 1
	v_permlane32_swap_b32 v130, v131
	s_waitcnt lgkmcnt(0)
	v_add_f32_e32 v130, v130, v131
	v_fmamk_f32 v132, v130, 0xbc800000, v49
	v_fmamk_f32 v134, v130, 0xbc800000, v47
	v_fmamk_f32 v131, v130, 0xbc800000, v48
	v_fmamk_f32 v133, v130, 0xbc800000, v46
	v_mul_f32_e32 v134, v134, v134
	v_mul_f32_e32 v132, v132, v132
	v_fmac_f32_e32 v134, v133, v133
	v_fmac_f32_e32 v132, v131, v131
	v_fmamk_f32 v133, v130, 0xbc800000, v45
	v_fmamk_f32 v135, v130, 0xbc800000, v43
	v_add_f32_e32 v131, v134, v132
	v_fmamk_f32 v132, v130, 0xbc800000, v44
	v_fmamk_f32 v134, v130, 0xbc800000, v42
	v_mul_f32_e32 v135, v135, v135
	v_mul_f32_e32 v133, v133, v133
	v_fmac_f32_e32 v135, v134, v134
	v_fmac_f32_e32 v133, v132, v132
	v_add_f32_e32 v132, v135, v133
	v_fmamk_f32 v133, v130, 0xbc800000, v41
	v_fmamk_f32 v135, v130, 0xbc800000, v39
	v_add_f32_e32 v131, v131, v132
	v_fmamk_f32 v132, v130, 0xbc800000, v40
	v_fmamk_f32 v134, v130, 0xbc800000, v38
	v_mul_f32_e32 v135, v135, v135
	v_mul_f32_e32 v133, v133, v133
	v_fmac_f32_e32 v135, v134, v134
	v_fmac_f32_e32 v133, v132, v132
	v_add_f32_e32 v132, v135, v133
	v_fmamk_f32 v133, v130, 0xbc800000, v37
	v_fmamk_f32 v135, v130, 0xbc800000, v35
	v_add_f32_e32 v131, v132, v131
	v_fmamk_f32 v132, v130, 0xbc800000, v36
	v_fmamk_f32 v134, v130, 0xbc800000, v34
	v_mul_f32_e32 v135, v135, v135
	v_mul_f32_e32 v133, v133, v133
	v_fmac_f32_e32 v135, v134, v134
	v_fmac_f32_e32 v133, v132, v132
	v_add_f32_e32 v132, v135, v133
	v_add_f32_e32 v131, v132, v131
	v_mov_b32_e32 v132, v131
	s_nop 1
	v_permlane16_swap_b32 v131, v132
	s_waitcnt lgkmcnt(0)
	v_add_f32_e32 v131, v131, v132
	ds_bpermute_b32 v132, v172, v131
	s_and_saveexec_b64 s[0:1], s[4:5]
	s_cbranch_execz .LBB0_1085
	s_lshl_b32 s3, s52, 11
	s_add_i32 s3, s29, s3
	v_mul_f32_e32 v130, 0x3c800000, v130
	v_lshl_add_u32 v133, v170, 5, s3
	s_waitcnt lgkmcnt(0)
	v_add_f32_e32 v131, v131, v132
	ds_write_b64 v133, v[130:131] offset:4608
;     __device__ __forceinline__ bool run(const f32x4 (&v)[2][2][4][2], const Unit& u, int wr, int wc, int fr, int fq, PG8_LAS unsigned char* lds, int wid, int lane) const {
;     ...
;             for (int m = 0; m < 4; ++m) {
;                 float s = 0.f;
; #pragma unroll
;                 for (int bj = 0; bj < 2; ++bj)
; #pragma unroll
;                     for (int n = 0; n < 2; ++n) { const f32x4 x = v[ai][bj][m][n]; s += (x[0] + x[1]) + (x[2] + x[3]); }
;                 s += __shfl_xor(s, 16); s += __shfl_xor(s, 32);
;                 const float mw = s * (1.0f / 64.0f); float q = 0.f;
; #pragma unroll
;                 for (int bj = 0; bj < 2; ++bj)
; #pragma unroll
;                     for (int n = 0; n < 2; ++n) { const f32x4 d = v[ai][bj][m][n] - mw; q += (d[0] * d[0] + d[1] * d[1]) + (d[2] * d[2] + d[3] * d[3]); }
;                 q += __shfl_xor(q, 16); q += __shfl_xor(q, 32);
;                 if (fq == 0) P[(ai * HALF + wr * 64 + m * 16 + fr) * 4 + wc] = (f32x2v){mw, q};
.LBB0_1085:
	s_or_b64 exec, exec, s[0:1]
	v_mov_b32_e32 v130, v31
	v_mov_b32_e32 v131, v32
	s_waitcnt lgkmcnt(0)
	v_mov_b32_e32 v132, v30
	v_mov_b32_e32 v133, v33
	v_pk_add_f32 v[130:131], v[130:131], v[132:133]
	v_mov_b32_e32 v132, v27
	v_mov_b32_e32 v133, v28
	v_mov_b32_e32 v134, v26
	v_mov_b32_e32 v135, v29
	v_pk_add_f32 v[132:133], v[132:133], v[134:135]
	v_add_f32_e32 v130, v130, v131
	v_pk_add_f32 v[132:133], v[132:133], v[132:133] op_sel_hi:[0,1]
	v_add_f32_e32 v131, 0, v130
	v_add_f32_e32 v135, v22, v23
	v_add_f32_e32 v137, v24, v25
	v_mov_b32_e32 v134, v18
	v_mov_b32_e32 v136, v19
	v_mov_b32_e32 v132, v20
	v_mov_b32_e32 v130, v21
	v_pk_add_f32 v[134:135], v[134:135], v[136:137]
	v_pk_add_f32 v[130:131], v[132:133], v[130:131]
	s_nop 0
	v_pk_add_f32 v[130:131], v[134:135], v[130:131]
	s_nop 0
	v_add_f32_e32 v130, v130, v131
	v_mov_b32_e32 v131, v130
	s_nop 1
	v_permlane16_swap_b32 v130, v131
	s_waitcnt lgkmcnt(0)
	v_add_f32_e32 v130, v130, v131
	v_mov_b32_e32 v131, v130
	s_nop 1
	v_permlane32_swap_b32 v130, v131
	s_waitcnt lgkmcnt(0)
	v_add_f32_e32 v130, v130, v131
	v_fmamk_f32 v132, v130, 0xbc800000, v33
	v_fmamk_f32 v134, v130, 0xbc800000, v31
	v_fmamk_f32 v131, v130, 0xbc800000, v32
	v_fmamk_f32 v133, v130, 0xbc800000, v30
	v_mul_f32_e32 v134, v134, v134
	v_mul_f32_e32 v132, v132, v132
	v_fmac_f32_e32 v134, v133, v133
	v_fmac_f32_e32 v132, v131, v131
	v_fmamk_f32 v133, v130, 0xbc800000, v29
	v_fmamk_f32 v135, v130, 0xbc800000, v27
	v_add_f32_e32 v131, v134, v132
	v_fmamk_f32 v132, v130, 0xbc800000, v28
	v_fmamk_f32 v134, v130, 0xbc800000, v26
	v_mul_f32_e32 v135, v135, v135
	v_mul_f32_e32 v133, v133, v133
	v_fmac_f32_e32 v135, v134, v134
	v_fmac_f32_e32 v133, v132, v132
	v_add_f32_e32 v132, v135, v133
	v_fmamk_f32 v133, v130, 0xbc800000, v25
	v_fmamk_f32 v135, v130, 0xbc800000, v23
	v_add_f32_e32 v131, v131, v132
	v_fmamk_f32 v132, v130, 0xbc800000, v24
	v_fmamk_f32 v134, v130, 0xbc800000, v22
	v_mul_f32_e32 v135, v135, v135
	v_mul_f32_e32 v133, v133, v133
	v_fmac_f32_e32 v135, v134, v134
	v_fmac_f32_e32 v133, v132, v132
	v_add_f32_e32 v132, v135, v133
	v_fmamk_f32 v133, v130, 0xbc800000, v21
	v_fmamk_f32 v135, v130, 0xbc800000, v19
	v_add_f32_e32 v131, v132, v131
	v_fmamk_f32 v132, v130, 0xbc800000, v20
	v_fmamk_f32 v134, v130, 0xbc800000, v18
	v_mul_f32_e32 v135, v135, v135
	v_mul_f32_e32 v133, v133, v133
	v_fmac_f32_e32 v135, v134, v134
	v_fmac_f32_e32 v133, v132, v132
	v_add_f32_e32 v132, v135, v133
	v_add_f32_e32 v131, v132, v131
	v_mov_b32_e32 v132, v131
	s_nop 1
	v_permlane16_swap_b32 v131, v132
	s_waitcnt lgkmcnt(0)
	v_add_f32_e32 v131, v131, v132
	ds_bpermute_b32 v132, v172, v131
	s_and_saveexec_b64 s[0:1], s[4:5]
	s_cbranch_execz .LBB0_1087
	s_lshl_b32 s3, s52, 11
	s_add_i32 s3, s29, s3
	v_mul_f32_e32 v130, 0x3c800000, v130
	v_lshl_add_u32 v133, v170, 5, s3
	s_waitcnt lgkmcnt(0)
	v_add_f32_e32 v131, v131, v132
	ds_write_b64 v133, v[130:131] offset:5120
.LBB0_1087:
	s_or_b64 exec, exec, s[0:1]
	v_mov_b32_e32 v130, v15
	v_mov_b32_e32 v131, v16
	s_waitcnt lgkmcnt(0)
	v_mov_b32_e32 v132, v14
	v_mov_b32_e32 v133, v17
	v_pk_add_f32 v[130:131], v[130:131], v[132:133]
	v_mov_b32_e32 v132, v11
	v_mov_b32_e32 v133, v12
	v_mov_b32_e32 v134, v10
	v_mov_b32_e32 v135, v13
	v_pk_add_f32 v[132:133], v[132:133], v[134:135]
	v_add_f32_e32 v130, v130, v131
	v_pk_add_f32 v[132:133], v[132:133], v[132:133] op_sel_hi:[0,1]
	v_add_f32_e32 v131, 0, v130
	v_add_f32_e32 v135, v6, v7
	v_add_f32_e32 v137, v8, v9
	v_mov_b32_e32 v134, v2
	v_mov_b32_e32 v136, v3
	v_mov_b32_e32 v132, v4
	v_mov_b32_e32 v130, v5
	v_pk_add_f32 v[134:135], v[134:135], v[136:137]
	v_pk_add_f32 v[130:131], v[132:133], v[130:131]
	s_nop 0
	v_pk_add_f32 v[130:131], v[134:135], v[130:131]
	s_nop 0
	v_add_f32_e32 v130, v130, v131
	v_mov_b32_e32 v131, v130
	s_nop 1
	v_permlane16_swap_b32 v130, v131
	s_waitcnt lgkmcnt(0)
	v_add_f32_e32 v130, v130, v131
	v_mov_b32_e32 v131, v130
	s_nop 1
	v_permlane32_swap_b32 v130, v131
	s_waitcnt lgkmcnt(0)
	v_add_f32_e32 v130, v130, v131
	v_fmamk_f32 v132, v130, 0xbc800000, v17
	v_fmamk_f32 v134, v130, 0xbc800000, v15
	v_fmamk_f32 v131, v130, 0xbc800000, v16
	v_fmamk_f32 v133, v130, 0xbc800000, v14
	v_mul_f32_e32 v134, v134, v134
	v_mul_f32_e32 v132, v132, v132
	v_fmac_f32_e32 v134, v133, v133
	v_fmac_f32_e32 v132, v131, v131
	v_fmamk_f32 v133, v130, 0xbc800000, v13
	v_fmamk_f32 v135, v130, 0xbc800000, v11
	v_add_f32_e32 v131, v134, v132
	v_fmamk_f32 v132, v130, 0xbc800000, v12
	v_fmamk_f32 v134, v130, 0xbc800000, v10
	v_mul_f32_e32 v135, v135, v135
	v_mul_f32_e32 v133, v133, v133
	v_fmac_f32_e32 v135, v134, v134
	v_fmac_f32_e32 v133, v132, v132
	v_add_f32_e32 v132, v135, v133
	v_fmamk_f32 v133, v130, 0xbc800000, v9
	v_fmamk_f32 v135, v130, 0xbc800000, v7
	v_add_f32_e32 v131, v131, v132
	v_fmamk_f32 v132, v130, 0xbc800000, v8
	v_fmamk_f32 v134, v130, 0xbc800000, v6
	v_mul_f32_e32 v135, v135, v135
	v_mul_f32_e32 v133, v133, v133
	v_fmac_f32_e32 v135, v134, v134
	v_fmac_f32_e32 v133, v132, v132
	v_add_f32_e32 v132, v135, v133
	v_fmamk_f32 v133, v130, 0xbc800000, v5
	v_fmamk_f32 v135, v130, 0xbc800000, v3
	v_add_f32_e32 v131, v132, v131
	v_fmamk_f32 v132, v130, 0xbc800000, v4
	v_fmamk_f32 v134, v130, 0xbc800000, v2
	v_mul_f32_e32 v135, v135, v135
	v_mul_f32_e32 v133, v133, v133
	v_fmac_f32_e32 v135, v134, v134
	v_fmac_f32_e32 v133, v132, v132
	v_add_f32_e32 v132, v135, v133
	v_add_f32_e32 v131, v132, v131
	v_mov_b32_e32 v132, v131
	s_nop 1
	v_permlane16_swap_b32 v131, v132
	s_waitcnt lgkmcnt(0)
	v_add_f32_e32 v131, v131, v132
	ds_bpermute_b32 v132, v172, v131
	s_and_saveexec_b64 s[0:1], s[4:5]
	s_cbranch_execz .LBB0_1089
	s_lshl_b32 s3, s52, 11
	s_add_i32 s29, s29, s3
	v_mul_f32_e32 v130, 0x3c800000, v130
	v_lshl_add_u32 v133, v170, 5, s29
	s_waitcnt lgkmcnt(0)
	v_add_f32_e32 v131, v131, v132
	ds_write_b64 v133, v[130:131] offset:5632

;     __device__ __forceinline__ bool run(const f32x4 (&v)[2][2][4][2], const Unit& u, int wr, int wc, int fr, int fq, PG8_LAS unsigned char* lds, int wid, int lane) const {
;     ...
;             for (int m = 0; m < 4; ++m) {
;                 float s = 0.f;
; #pragma unroll
;                 for (int bj = 0; bj < 2; ++bj)
; #pragma unroll
;                     for (int n = 0; n < 2; ++n) { const f32x4 x = v[ai][bj][m][n]; s += (x[0] + x[1]) + (x[2] + x[3]); }
;                 s += __shfl_xor(s, 16); s += __shfl_xor(s, 32);
;                 const float mw = s * (1.0f / 64.0f); float q = 0.f;
; #pragma unroll
;                 for (int bj = 0; bj < 2; ++bj)
; #pragma unroll
;                     for (int n = 0; n < 2; ++n) { const f32x4 d = v[ai][bj][m][n] - mw; q += (d[0] * d[0] + d[1] * d[1]) + (d[2] * d[2] + d[3] * d[3]); }
;                 q += __shfl_xor(q, 16); q += __shfl_xor(q, 32);
;                 if (fq == 0) P[(ai * HALF + wr * 64 + m * 16 + fr) * 4 + wc] = (f32x2v){mw, q};
.LBB0_1266:
	s_or_b64 exec, exec, s[0:1]
	v_mov_b32_e32 v222, v115
	s_waitcnt lgkmcnt(0)
	v_mov_b32_e32 v223, v116
	v_mov_b32_e32 v224, v114
	v_mov_b32_e32 v225, v117
	v_pk_add_f32 v[222:223], v[222:223], v[224:225]
	v_mov_b32_e32 v224, v107
	v_mov_b32_e32 v225, v108
	v_mov_b32_e32 v226, v106
	v_mov_b32_e32 v227, v109
	v_pk_add_f32 v[224:225], v[224:225], v[226:227]
	v_add_f32_e32 v221, v222, v223
	v_pk_add_f32 v[224:225], v[224:225], v[224:225] op_sel_hi:[0,1]
	v_add_f32_e32 v223, 0, v221
	v_add_f32_e32 v227, v102, v103
	v_add_f32_e32 v229, v104, v105
	v_mov_b32_e32 v226, v94
	v_mov_b32_e32 v228, v95
	v_mov_b32_e32 v224, v96
	v_mov_b32_e32 v222, v97
	v_pk_add_f32 v[226:227], v[226:227], v[228:229]
	v_pk_add_f32 v[222:223], v[224:225], v[222:223]
	v_mov_b32_e32 v225, v115
	v_pk_add_f32 v[222:223], v[226:227], v[222:223]
	v_mov_b32_e32 v224, v114
	v_add_f32_e32 v221, v222, v223
	ds_bpermute_b32 v222, v216, v221
	v_mov_b32_e32 v226, v107
	s_waitcnt lgkmcnt(0)
	v_add_f32_e32 v221, v221, v222
	v_mov_b32_e32 v222, v221
	s_nop 1
	v_permlane32_swap_b32 v221, v222
	s_waitcnt lgkmcnt(0)
	v_add_f32_e32 v221, v221, v222
	v_fmamk_f32 v223, v221, 0xbc800000, v117
	v_fmac_f32_e32 v225, 0xbc800000, v221
	v_fmamk_f32 v222, v221, 0xbc800000, v116
	v_fmac_f32_e32 v224, 0xbc800000, v221
	v_mul_f32_e32 v225, v225, v225
	v_mul_f32_e32 v223, v223, v223
	v_fmac_f32_e32 v225, v224, v224
	v_fmac_f32_e32 v223, v222, v222
	v_add_f32_e32 v222, v225, v223
	v_fmamk_f32 v224, v221, 0xbc800000, v109
	v_mov_b32_e32 v225, v106
	v_fmac_f32_e32 v226, 0xbc800000, v221
	v_fmamk_f32 v223, v221, 0xbc800000, v108
	v_fmac_f32_e32 v225, 0xbc800000, v221
	v_mul_f32_e32 v226, v226, v226
	v_mul_f32_e32 v224, v224, v224
	v_fmac_f32_e32 v226, v225, v225
	v_fmac_f32_e32 v224, v223, v223
	v_add_f32_e32 v223, v226, v224
	v_mov_b32_e32 v226, v103
	v_fmamk_f32 v224, v221, 0xbc800000, v105
	v_mov_b32_e32 v225, v102
	v_fmac_f32_e32 v226, 0xbc800000, v221
	v_add_f32_e32 v222, v222, v223
	v_fmamk_f32 v223, v221, 0xbc800000, v104
	v_fmac_f32_e32 v225, 0xbc800000, v221
	v_mul_f32_e32 v226, v226, v226
	v_mul_f32_e32 v224, v224, v224
	v_fmac_f32_e32 v226, v225, v225
	v_fmac_f32_e32 v224, v223, v223
	v_add_f32_e32 v223, v226, v224
	v_mov_b32_e32 v226, v95
	v_fmamk_f32 v224, v221, 0xbc800000, v97
	v_mov_b32_e32 v225, v94
	v_fmac_f32_e32 v226, 0xbc800000, v221
	v_add_f32_e32 v222, v223, v222
	v_fmamk_f32 v223, v221, 0xbc800000, v96
	v_fmac_f32_e32 v225, 0xbc800000, v221
	v_mul_f32_e32 v226, v226, v226
	v_mul_f32_e32 v224, v224, v224
	v_fmac_f32_e32 v226, v225, v225
	v_fmac_f32_e32 v224, v223, v223
	v_add_f32_e32 v223, v226, v224
	v_add_f32_e32 v222, v223, v222
	v_mov_b32_e32 v223, v222
	s_nop 1
	v_permlane16_swap_b32 v222, v223
	s_waitcnt lgkmcnt(0)
	v_add_f32_e32 v222, v222, v223
	ds_bpermute_b32 v223, v220, v222
	s_and_saveexec_b64 s[0:1], vcc
	s_cbranch_execz .LBB0_1268
	s_lshl_b32 s4, s13, 11
	s_add_i32 s4, s2, s4
	v_mul_f32_e32 v224, 0x3c800000, v221
	v_lshl_add_u32 v221, v1, 5, s4
	s_waitcnt lgkmcnt(0)
	v_add_f32_e32 v225, v222, v223
	ds_write_b64 v221, v[224:225] offset:512
.LBB0_1268:
	s_or_b64 exec, exec, s[0:1]
	v_mov_b32_e32 v222, v99
	s_waitcnt lgkmcnt(0)
	v_mov_b32_e32 v223, v100
	v_mov_b32_e32 v224, v98
	v_mov_b32_e32 v225, v101
	v_pk_add_f32 v[222:223], v[222:223], v[224:225]
	v_mov_b32_e32 v224, v91
	v_mov_b32_e32 v225, v92
	v_mov_b32_e32 v226, v90
	v_mov_b32_e32 v227, v93
	v_pk_add_f32 v[224:225], v[224:225], v[226:227]
	v_add_f32_e32 v221, v222, v223
	v_pk_add_f32 v[224:225], v[224:225], v[224:225] op_sel_hi:[0,1]
	v_add_f32_e32 v223, 0, v221
	v_add_f32_e32 v227, v86, v87
	v_add_f32_e32 v229, v88, v89
	v_mov_b32_e32 v226, v78
	v_mov_b32_e32 v228, v79
	v_mov_b32_e32 v224, v80
	v_mov_b32_e32 v222, v81
	v_pk_add_f32 v[226:227], v[226:227], v[228:229]
	v_pk_add_f32 v[222:223], v[224:225], v[222:223]
	v_mov_b32_e32 v225, v99
	v_pk_add_f32 v[222:223], v[226:227], v[222:223]
	v_mov_b32_e32 v224, v98
	v_add_f32_e32 v221, v222, v223
	ds_bpermute_b32 v222, v216, v221
	v_mov_b32_e32 v226, v91
	s_waitcnt lgkmcnt(0)
	v_add_f32_e32 v221, v221, v222
	v_mov_b32_e32 v222, v221
	s_nop 1
	v_permlane32_swap_b32 v221, v222
	s_waitcnt lgkmcnt(0)
	v_add_f32_e32 v221, v221, v222
	v_fmamk_f32 v223, v221, 0xbc800000, v101
	v_fmac_f32_e32 v225, 0xbc800000, v221
	v_fmamk_f32 v222, v221, 0xbc800000, v100
	v_fmac_f32_e32 v224, 0xbc800000, v221
	v_mul_f32_e32 v225, v225, v225
	v_mul_f32_e32 v223, v223, v223
	v_fmac_f32_e32 v225, v224, v224
	v_fmac_f32_e32 v223, v222, v222
	v_add_f32_e32 v222, v225, v223
	v_fmamk_f32 v224, v221, 0xbc800000, v93
	v_mov_b32_e32 v225, v90
	v_fmac_f32_e32 v226, 0xbc800000, v221
	v_fmamk_f32 v223, v221, 0xbc800000, v92
	v_fmac_f32_e32 v225, 0xbc800000, v221
	v_mul_f32_e32 v226, v226, v226
	v_mul_f32_e32 v224, v224, v224
	v_fmac_f32_e32 v226, v225, v225
	v_fmac_f32_e32 v224, v223, v223
	v_add_f32_e32 v223, v226, v224
	v_mov_b32_e32 v226, v87
	v_fmamk_f32 v224, v221, 0xbc800000, v89
	v_mov_b32_e32 v225, v86
	v_fmac_f32_e32 v226, 0xbc800000, v221
	v_add_f32_e32 v222, v222, v223
	v_fmamk_f32 v223, v221, 0xbc800000, v88
	v_fmac_f32_e32 v225, 0xbc800000, v221
	v_mul_f32_e32 v226, v226, v226
	v_mul_f32_e32 v224, v224, v224
	v_fmac_f32_e32 v226, v225, v225
	v_fmac_f32_e32 v224, v223, v223
	v_add_f32_e32 v223, v226, v224
	v_mov_b32_e32 v226, v79
	v_fmamk_f32 v224, v221, 0xbc800000, v81
	v_mov_b32_e32 v225, v78
	v_fmac_f32_e32 v226, 0xbc800000, v221
	v_add_f32_e32 v222, v223, v222
	v_fmamk_f32 v223, v221, 0xbc800000, v80
	v_fmac_f32_e32 v225, 0xbc800000, v221
	v_mul_f32_e32 v226, v226, v226
	v_mul_f32_e32 v224, v224, v224
	v_fmac_f32_e32 v226, v225, v225
	v_fmac_f32_e32 v224, v223, v223
	v_add_f32_e32 v223, v226, v224
	v_add_f32_e32 v222, v223, v222
	v_mov_b32_e32 v223, v222
	s_nop 1
	v_permlane16_swap_b32 v222, v223
	s_waitcnt lgkmcnt(0)
	v_add_f32_e32 v222, v222, v223
	ds_bpermute_b32 v223, v220, v222
	s_and_saveexec_b64 s[0:1], vcc
	s_cbranch_execz .LBB0_1270
	s_lshl_b32 s4, s13, 11
	s_add_i32 s4, s2, s4
	v_mul_f32_e32 v224, 0x3c800000, v221
	v_lshl_add_u32 v221, v1, 5, s4
	s_waitcnt lgkmcnt(0)
	v_add_f32_e32 v225, v222, v223
	ds_write_b64 v221, v[224:225] offset:1024
;     __device__ __forceinline__ bool run(const f32x4 (&v)[2][2][4][2], const Unit& u, int wr, int wc, int fr, int fq, PG8_LAS unsigned char* lds, int wid, int lane) const {
;     ...
;             for (int m = 0; m < 4; ++m) {
;                 float s = 0.f;
; #pragma unroll
;                 for (int bj = 0; bj < 2; ++bj)
; #pragma unroll
;                     for (int n = 0; n < 2; ++n) { const f32x4 x = v[ai][bj][m][n]; s += (x[0] + x[1]) + (x[2] + x[3]); }
;                 s += __shfl_xor(s, 16); s += __shfl_xor(s, 32);
;                 const float mw = s * (1.0f / 64.0f); float q = 0.f;
; #pragma unroll
;                 for (int bj = 0; bj < 2; ++bj)
; #pragma unroll
;                     for (int n = 0; n < 2; ++n) { const f32x4 d = v[ai][bj][m][n] - mw; q += (d[0] * d[0] + d[1] * d[1]) + (d[2] * d[2] + d[3] * d[3]); }
;                 q += __shfl_xor(q, 16); q += __shfl_xor(q, 32);
;                 if (fq == 0) P[(ai * HALF + wr * 64 + m * 16 + fr) * 4 + wc] = (f32x2v){mw, q};
.LBB0_1270:
	s_or_b64 exec, exec, s[0:1]
	v_mov_b32_e32 v222, v83
	s_waitcnt lgkmcnt(0)
	v_mov_b32_e32 v223, v84
	v_mov_b32_e32 v224, v82
	v_mov_b32_e32 v225, v85
	v_pk_add_f32 v[222:223], v[222:223], v[224:225]
	v_mov_b32_e32 v224, v75
	v_mov_b32_e32 v225, v76
	v_mov_b32_e32 v226, v74
	v_mov_b32_e32 v227, v77
	v_pk_add_f32 v[224:225], v[224:225], v[226:227]
	v_add_f32_e32 v221, v222, v223
	v_pk_add_f32 v[224:225], v[224:225], v[224:225] op_sel_hi:[0,1]
	v_add_f32_e32 v223, 0, v221
	v_add_f32_e32 v227, v70, v71
	v_add_f32_e32 v229, v72, v73
	v_mov_b32_e32 v226, v66
	v_mov_b32_e32 v228, v67
	v_mov_b32_e32 v224, v68
	v_mov_b32_e32 v222, v69
	v_pk_add_f32 v[226:227], v[226:227], v[228:229]
	v_pk_add_f32 v[222:223], v[224:225], v[222:223]
	v_mov_b32_e32 v225, v83
	v_pk_add_f32 v[222:223], v[226:227], v[222:223]
	v_mov_b32_e32 v224, v82
	v_add_f32_e32 v221, v222, v223
	ds_bpermute_b32 v222, v216, v221
	v_mov_b32_e32 v226, v75
	s_waitcnt lgkmcnt(0)
	v_add_f32_e32 v221, v221, v222
	v_mov_b32_e32 v222, v221
	s_nop 1
	v_permlane32_swap_b32 v221, v222
	s_waitcnt lgkmcnt(0)
	v_add_f32_e32 v221, v221, v222
	v_fmamk_f32 v223, v221, 0xbc800000, v85
	v_fmac_f32_e32 v225, 0xbc800000, v221
	v_fmamk_f32 v222, v221, 0xbc800000, v84
	v_fmac_f32_e32 v224, 0xbc800000, v221
	v_mul_f32_e32 v225, v225, v225
	v_mul_f32_e32 v223, v223, v223
	v_fmac_f32_e32 v225, v224, v224
	v_fmac_f32_e32 v223, v222, v222
	v_add_f32_e32 v222, v225, v223
	v_fmamk_f32 v224, v221, 0xbc800000, v77
	v_mov_b32_e32 v225, v74
	v_fmac_f32_e32 v226, 0xbc800000, v221
	v_fmamk_f32 v223, v221, 0xbc800000, v76
	v_fmac_f32_e32 v225, 0xbc800000, v221
	v_mul_f32_e32 v226, v226, v226
	v_mul_f32_e32 v224, v224, v224
	v_fmac_f32_e32 v226, v225, v225
	v_fmac_f32_e32 v224, v223, v223
	v_add_f32_e32 v223, v226, v224
	v_mov_b32_e32 v226, v71
	v_fmamk_f32 v224, v221, 0xbc800000, v73
	v_mov_b32_e32 v225, v70
	v_fmac_f32_e32 v226, 0xbc800000, v221
	v_add_f32_e32 v222, v222, v223
	v_fmamk_f32 v223, v221, 0xbc800000, v72
	v_fmac_f32_e32 v225, 0xbc800000, v221
	v_mul_f32_e32 v226, v226, v226
	v_mul_f32_e32 v224, v224, v224
	v_fmac_f32_e32 v226, v225, v225
	v_fmac_f32_e32 v224, v223, v223
	v_add_f32_e32 v223, v226, v224
	v_mov_b32_e32 v226, v67
	v_fmamk_f32 v224, v221, 0xbc800000, v69
	v_mov_b32_e32 v225, v66
	v_fmac_f32_e32 v226, 0xbc800000, v221
	v_add_f32_e32 v222, v223, v222
	v_fmamk_f32 v223, v221, 0xbc800000, v68
	v_fmac_f32_e32 v225, 0xbc800000, v221
	v_mul_f32_e32 v226, v226, v226
	v_mul_f32_e32 v224, v224, v224
	v_fmac_f32_e32 v226, v225, v225
	v_fmac_f32_e32 v224, v223, v223
	v_add_f32_e32 v223, v226, v224
	v_add_f32_e32 v222, v223, v222
	v_mov_b32_e32 v223, v222
	s_nop 1
	v_permlane16_swap_b32 v222, v223
	s_waitcnt lgkmcnt(0)
	v_add_f32_e32 v222, v222, v223
	ds_bpermute_b32 v223, v220, v222
	s_and_saveexec_b64 s[0:1], vcc
	s_cbranch_execz .LBB0_1272
	s_lshl_b32 s4, s13, 11
	s_add_i32 s4, s2, s4
	v_mul_f32_e32 v224, 0x3c800000, v221
	v_lshl_add_u32 v221, v1, 5, s4
	s_waitcnt lgkmcnt(0)
	v_add_f32_e32 v225, v222, v223
	ds_write_b64 v221, v[224:225] offset:1536
.LBB0_1272:
	s_or_b64 exec, exec, s[0:1]
	v_mov_b32_e32 v222, v63
	s_waitcnt lgkmcnt(0)
	v_mov_b32_e32 v223, v64
	v_mov_b32_e32 v224, v62
	v_mov_b32_e32 v225, v65
	v_pk_add_f32 v[222:223], v[222:223], v[224:225]
	v_mov_b32_e32 v224, v59
	v_mov_b32_e32 v225, v60
	v_mov_b32_e32 v226, v58
	v_mov_b32_e32 v227, v61
	v_pk_add_f32 v[224:225], v[224:225], v[226:227]
	v_add_f32_e32 v221, v222, v223
	v_pk_add_f32 v[224:225], v[224:225], v[224:225] op_sel_hi:[0,1]
	v_add_f32_e32 v223, 0, v221
	v_add_f32_e32 v227, v54, v55
	v_add_f32_e32 v229, v56, v57
	v_mov_b32_e32 v226, v46
	v_mov_b32_e32 v228, v47
	v_mov_b32_e32 v224, v48
	v_mov_b32_e32 v222, v49
	v_pk_add_f32 v[226:227], v[226:227], v[228:229]
	v_pk_add_f32 v[222:223], v[224:225], v[222:223]
	v_mov_b32_e32 v225, v63
	v_pk_add_f32 v[222:223], v[226:227], v[222:223]
	v_mov_b32_e32 v224, v62
	v_add_f32_e32 v221, v222, v223
	ds_bpermute_b32 v222, v216, v221
	v_mov_b32_e32 v226, v59
	s_waitcnt lgkmcnt(0)
	v_add_f32_e32 v221, v221, v222
	v_mov_b32_e32 v222, v221
	s_nop 1
	v_permlane32_swap_b32 v221, v222
	s_waitcnt lgkmcnt(0)
	v_add_f32_e32 v221, v221, v222
	v_fmamk_f32 v223, v221, 0xbc800000, v65
	v_fmac_f32_e32 v225, 0xbc800000, v221
	v_fmamk_f32 v222, v221, 0xbc800000, v64
	v_fmac_f32_e32 v224, 0xbc800000, v221
	v_mul_f32_e32 v225, v225, v225
	v_mul_f32_e32 v223, v223, v223
	v_fmac_f32_e32 v225, v224, v224
	v_fmac_f32_e32 v223, v222, v222
	v_add_f32_e32 v222, v225, v223
	v_fmamk_f32 v224, v221, 0xbc800000, v61
	v_mov_b32_e32 v225, v58
	v_fmac_f32_e32 v226, 0xbc800000, v221
	v_fmamk_f32 v223, v221, 0xbc800000, v60
	v_fmac_f32_e32 v225, 0xbc800000, v221
	v_mul_f32_e32 v226, v226, v226
	v_mul_f32_e32 v224, v224, v224
	v_fmac_f32_e32 v226, v225, v225
	v_fmac_f32_e32 v224, v223, v223
	v_add_f32_e32 v223, v226, v224
	v_mov_b32_e32 v226, v55
	v_fmamk_f32 v224, v221, 0xbc800000, v57
	v_mov_b32_e32 v225, v54
	v_fmac_f32_e32 v226, 0xbc800000, v221
	v_add_f32_e32 v222, v222, v223
	v_fmamk_f32 v223, v221, 0xbc800000, v56
	v_fmac_f32_e32 v225, 0xbc800000, v221
	v_mul_f32_e32 v226, v226, v226
	v_mul_f32_e32 v224, v224, v224
	v_fmac_f32_e32 v226, v225, v225
	v_fmac_f32_e32 v224, v223, v223
	v_add_f32_e32 v223, v226, v224
	v_mov_b32_e32 v226, v47
	v_fmamk_f32 v224, v221, 0xbc800000, v49
	v_mov_b32_e32 v225, v46
	v_fmac_f32_e32 v226, 0xbc800000, v221
	v_add_f32_e32 v222, v223, v222
	v_fmamk_f32 v223, v221, 0xbc800000, v48
	v_fmac_f32_e32 v225, 0xbc800000, v221
	v_mul_f32_e32 v226, v226, v226
	v_mul_f32_e32 v224, v224, v224
	v_fmac_f32_e32 v226, v225, v225
	v_fmac_f32_e32 v224, v223, v223
	v_add_f32_e32 v223, v226, v224
	v_add_f32_e32 v222, v223, v222
	v_mov_b32_e32 v223, v222
	s_nop 1
	v_permlane16_swap_b32 v222, v223
	s_waitcnt lgkmcnt(0)
	v_add_f32_e32 v222, v222, v223
	ds_bpermute_b32 v223, v220, v222
	s_and_saveexec_b64 s[0:1], vcc
	s_cbranch_execz .LBB0_1274
	s_lshl_b32 s4, s13, 11
	s_add_i32 s4, s2, s4
	v_mul_f32_e32 v224, 0x3c800000, v221
	v_lshl_add_u32 v221, v1, 5, s4
	s_waitcnt lgkmcnt(0)
	v_add_f32_e32 v225, v222, v223
	ds_write_b64 v221, v[224:225] offset:4096
;     __device__ __forceinline__ bool run(const f32x4 (&v)[2][2][4][2], const Unit& u, int wr, int wc, int fr, int fq, PG8_LAS unsigned char* lds, int wid, int lane) const {
;     ...
;             for (int m = 0; m < 4; ++m) {
;                 float s = 0.f;
; #pragma unroll
;                 for (int bj = 0; bj < 2; ++bj)
; #pragma unroll
;                     for (int n = 0; n < 2; ++n) { const f32x4 x = v[ai][bj][m][n]; s += (x[0] + x[1]) + (x[2] + x[3]); }
;                 s += __shfl_xor(s, 16); s += __shfl_xor(s, 32);
;                 const float mw = s * (1.0f / 64.0f); float q = 0.f;
; #pragma unroll
;                 for (int bj = 0; bj < 2; ++bj)
; #pragma unroll
;                     for (int n = 0; n < 2; ++n) { const f32x4 d = v[ai][bj][m][n] - mw; q += (d[0] * d[0] + d[1] * d[1]) + (d[2] * d[2] + d[3] * d[3]); }
;                 q += __shfl_xor(q, 16); q += __shfl_xor(q, 32);
;                 if (fq == 0) P[(ai * HALF + wr * 64 + m * 16 + fr) * 4 + wc] = (f32x2v){mw, q};
.LBB0_1274:
	s_or_b64 exec, exec, s[0:1]
	v_mov_b32_e32 v222, v51
	s_waitcnt lgkmcnt(0)
	v_mov_b32_e32 v223, v52
	v_mov_b32_e32 v224, v50
	v_mov_b32_e32 v225, v53
	v_pk_add_f32 v[222:223], v[222:223], v[224:225]
	v_mov_b32_e32 v224, v43
	v_mov_b32_e32 v225, v44
	v_mov_b32_e32 v226, v42
	v_mov_b32_e32 v227, v45
	v_pk_add_f32 v[224:225], v[224:225], v[226:227]
	v_add_f32_e32 v221, v222, v223
	v_pk_add_f32 v[224:225], v[224:225], v[224:225] op_sel_hi:[0,1]
	v_add_f32_e32 v223, 0, v221
	v_add_f32_e32 v227, v38, v39
	v_add_f32_e32 v229, v40, v41
	v_mov_b32_e32 v226, v30
	v_mov_b32_e32 v228, v31
	v_mov_b32_e32 v224, v32
	v_mov_b32_e32 v222, v33
	v_pk_add_f32 v[226:227], v[226:227], v[228:229]
	v_pk_add_f32 v[222:223], v[224:225], v[222:223]
	v_mov_b32_e32 v225, v51
	v_pk_add_f32 v[222:223], v[226:227], v[222:223]
	v_mov_b32_e32 v224, v50
	v_add_f32_e32 v221, v222, v223
	ds_bpermute_b32 v222, v216, v221
	v_mov_b32_e32 v226, v43
	s_waitcnt lgkmcnt(0)
	v_add_f32_e32 v221, v221, v222
	v_mov_b32_e32 v222, v221
	s_nop 1
	v_permlane32_swap_b32 v221, v222
	s_waitcnt lgkmcnt(0)
	v_add_f32_e32 v221, v221, v222
	v_fmamk_f32 v223, v221, 0xbc800000, v53
	v_fmac_f32_e32 v225, 0xbc800000, v221
	v_fmamk_f32 v222, v221, 0xbc800000, v52
	v_fmac_f32_e32 v224, 0xbc800000, v221
	v_mul_f32_e32 v225, v225, v225
	v_mul_f32_e32 v223, v223, v223
	v_fmac_f32_e32 v225, v224, v224
	v_fmac_f32_e32 v223, v222, v222
	v_add_f32_e32 v222, v225, v223
	v_fmamk_f32 v224, v221, 0xbc800000, v45
	v_mov_b32_e32 v225, v42
	v_fmac_f32_e32 v226, 0xbc800000, v221
	v_fmamk_f32 v223, v221, 0xbc800000, v44
	v_fmac_f32_e32 v225, 0xbc800000, v221
	v_mul_f32_e32 v226, v226, v226
	v_mul_f32_e32 v224, v224, v224
	v_fmac_f32_e32 v226, v225, v225
	v_fmac_f32_e32 v224, v223, v223
	v_add_f32_e32 v223, v226, v224
	v_mov_b32_e32 v226, v39
	v_fmamk_f32 v224, v221, 0xbc800000, v41
	v_mov_b32_e32 v225, v38
	v_fmac_f32_e32 v226, 0xbc800000, v221
	v_add_f32_e32 v222, v222, v223
	v_fmamk_f32 v223, v221, 0xbc800000, v40
	v_fmac_f32_e32 v225, 0xbc800000, v221
	v_mul_f32_e32 v226, v226, v226
	v_mul_f32_e32 v224, v224, v224
	v_fmac_f32_e32 v226, v225, v225
	v_fmac_f32_e32 v224, v223, v223
	v_add_f32_e32 v223, v226, v224
	v_mov_b32_e32 v226, v31
	v_fmamk_f32 v224, v221, 0xbc800000, v33
	v_mov_b32_e32 v225, v30
	v_fmac_f32_e32 v226, 0xbc800000, v221
	v_add_f32_e32 v222, v223, v222
	v_fmamk_f32 v223, v221, 0xbc800000, v32
	v_fmac_f32_e32 v225, 0xbc800000, v221
	v_mul_f32_e32 v226, v226, v226
	v_mul_f32_e32 v224, v224, v224
	v_fmac_f32_e32 v226, v225, v225
	v_fmac_f32_e32 v224, v223, v223
	v_add_f32_e32 v223, v226, v224
	v_add_f32_e32 v222, v223, v222
	v_mov_b32_e32 v223, v222
	s_nop 1
	v_permlane16_swap_b32 v222, v223
	s_waitcnt lgkmcnt(0)
	v_add_f32_e32 v222, v222, v223
	ds_bpermute_b32 v223, v220, v222
	s_and_saveexec_b64 s[0:1], vcc
	s_cbranch_execz .LBB0_1276
	s_lshl_b32 s4, s13, 11
	s_add_i32 s4, s2, s4
	v_mul_f32_e32 v224, 0x3c800000, v221
	v_lshl_add_u32 v221, v1, 5, s4
	s_waitcnt lgkmcnt(0)
	v_add_f32_e32 v225, v222, v223
	ds_write_b64 v221, v[224:225] offset:4608
;     __device__ __forceinline__ bool run(const f32x4 (&v)[2][2][4][2], const Unit& u, int wr, int wc, int fr, int fq, PG8_LAS unsigned char* lds, int wid, int lane) const {
;     ...
;             for (int m = 0; m < 4; ++m) {
;                 float s = 0.f;
; #pragma unroll
;                 for (int bj = 0; bj < 2; ++bj)
; #pragma unroll
;                     for (int n = 0; n < 2; ++n) { const f32x4 x = v[ai][bj][m][n]; s += (x[0] + x[1]) + (x[2] + x[3]); }
;                 s += __shfl_xor(s, 16); s += __shfl_xor(s, 32);
;                 const float mw = s * (1.0f / 64.0f); float q = 0.f;
; #pragma unroll
;                 for (int bj = 0; bj < 2; ++bj)
; #pragma unroll
;                     for (int n = 0; n < 2; ++n) { const f32x4 d = v[ai][bj][m][n] - mw; q += (d[0] * d[0] + d[1] * d[1]) + (d[2] * d[2] + d[3] * d[3]); }
;                 q += __shfl_xor(q, 16); q += __shfl_xor(q, 32);
;                 if (fq == 0) P[(ai * HALF + wr * 64 + m * 16 + fr) * 4 + wc] = (f32x2v){mw, q};
.LBB0_1276:
	s_or_b64 exec, exec, s[0:1]
	v_mov_b32_e32 v222, v35
	s_waitcnt lgkmcnt(0)
	v_mov_b32_e32 v223, v36
	v_mov_b32_e32 v224, v34
	v_mov_b32_e32 v225, v37
	v_pk_add_f32 v[222:223], v[222:223], v[224:225]
	v_mov_b32_e32 v224, v27
	v_mov_b32_e32 v225, v28
	v_mov_b32_e32 v226, v26
	v_mov_b32_e32 v227, v29
	v_pk_add_f32 v[224:225], v[224:225], v[226:227]
	v_add_f32_e32 v221, v222, v223
	v_pk_add_f32 v[224:225], v[224:225], v[224:225] op_sel_hi:[0,1]
	v_add_f32_e32 v223, 0, v221
	v_add_f32_e32 v227, v22, v23
	v_add_f32_e32 v229, v24, v25
	v_mov_b32_e32 v226, v14
	v_mov_b32_e32 v228, v15
	v_mov_b32_e32 v224, v16
	v_mov_b32_e32 v222, v17
	v_pk_add_f32 v[226:227], v[226:227], v[228:229]
	v_pk_add_f32 v[222:223], v[224:225], v[222:223]
	v_mov_b32_e32 v225, v35
	v_pk_add_f32 v[222:223], v[226:227], v[222:223]
	v_mov_b32_e32 v224, v34
	v_add_f32_e32 v221, v222, v223
	ds_bpermute_b32 v222, v216, v221
	v_mov_b32_e32 v226, v27
	s_waitcnt lgkmcnt(0)
	v_add_f32_e32 v221, v221, v222
	v_mov_b32_e32 v222, v221
	s_nop 1
	v_permlane32_swap_b32 v221, v222
	s_waitcnt lgkmcnt(0)
	v_add_f32_e32 v221, v221, v222
	v_fmamk_f32 v223, v221, 0xbc800000, v37
	v_fmac_f32_e32 v225, 0xbc800000, v221
	v_fmamk_f32 v222, v221, 0xbc800000, v36
	v_fmac_f32_e32 v224, 0xbc800000, v221
	v_mul_f32_e32 v225, v225, v225
	v_mul_f32_e32 v223, v223, v223
	v_fmac_f32_e32 v225, v224, v224
	v_fmac_f32_e32 v223, v222, v222
	v_add_f32_e32 v222, v225, v223
	v_fmamk_f32 v224, v221, 0xbc800000, v29
	v_mov_b32_e32 v225, v26
	v_fmac_f32_e32 v226, 0xbc800000, v221
	v_fmamk_f32 v223, v221, 0xbc800000, v28
	v_fmac_f32_e32 v225, 0xbc800000, v221
	v_mul_f32_e32 v226, v226, v226
	v_mul_f32_e32 v224, v224, v224
	v_fmac_f32_e32 v226, v225, v225
	v_fmac_f32_e32 v224, v223, v223
	v_add_f32_e32 v223, v226, v224
	v_mov_b32_e32 v226, v23
	v_fmamk_f32 v224, v221, 0xbc800000, v25
	v_mov_b32_e32 v225, v22
	v_fmac_f32_e32 v226, 0xbc800000, v221
	v_add_f32_e32 v222, v222, v223
	v_fmamk_f32 v223, v221, 0xbc800000, v24
	v_fmac_f32_e32 v225, 0xbc800000, v221
	v_mul_f32_e32 v226, v226, v226
	v_mul_f32_e32 v224, v224, v224
	v_fmac_f32_e32 v226, v225, v225
	v_fmac_f32_e32 v224, v223, v223
	v_add_f32_e32 v223, v226, v224
	v_mov_b32_e32 v226, v15
	v_fmamk_f32 v224, v221, 0xbc800000, v17
	v_mov_b32_e32 v225, v14
	v_fmac_f32_e32 v226, 0xbc800000, v221
	v_add_f32_e32 v222, v223, v222
	v_fmamk_f32 v223, v221, 0xbc800000, v16
	v_fmac_f32_e32 v225, 0xbc800000, v221
	v_mul_f32_e32 v226, v226, v226
	v_mul_f32_e32 v224, v224, v224
	v_fmac_f32_e32 v226, v225, v225
	v_fmac_f32_e32 v224, v223, v223
	v_add_f32_e32 v223, v226, v224
	v_add_f32_e32 v222, v223, v222
	v_mov_b32_e32 v223, v222
	s_nop 1
	v_permlane16_swap_b32 v222, v223
	s_waitcnt lgkmcnt(0)
	v_add_f32_e32 v222, v222, v223
	ds_bpermute_b32 v223, v220, v222
	s_and_saveexec_b64 s[0:1], vcc
	s_cbranch_execz .LBB0_1278
	s_lshl_b32 s4, s13, 11
	s_add_i32 s4, s2, s4
	v_mul_f32_e32 v224, 0x3c800000, v221
	v_lshl_add_u32 v221, v1, 5, s4
	s_waitcnt lgkmcnt(0)
	v_add_f32_e32 v225, v222, v223
	ds_write_b64 v221, v[224:225] offset:5120
.LBB0_1278:
	s_or_b64 exec, exec, s[0:1]
	v_mov_b32_e32 v222, v19
	s_waitcnt lgkmcnt(0)
	v_mov_b32_e32 v223, v20
	v_mov_b32_e32 v224, v18
	v_mov_b32_e32 v225, v21
	v_pk_add_f32 v[222:223], v[222:223], v[224:225]
	v_mov_b32_e32 v224, v11
	v_mov_b32_e32 v225, v12
	v_mov_b32_e32 v226, v10
	v_mov_b32_e32 v227, v13
	v_pk_add_f32 v[224:225], v[224:225], v[226:227]
	v_add_f32_e32 v221, v222, v223
	v_pk_add_f32 v[224:225], v[224:225], v[224:225] op_sel_hi:[0,1]
	v_add_f32_e32 v223, 0, v221
	v_add_f32_e32 v227, v6, v7
	v_add_f32_e32 v229, v8, v9
	v_mov_b32_e32 v226, v2
	v_mov_b32_e32 v228, v3
	v_mov_b32_e32 v224, v4
	v_mov_b32_e32 v222, v5
	v_pk_add_f32 v[226:227], v[226:227], v[228:229]
	v_pk_add_f32 v[222:223], v[224:225], v[222:223]
	v_mov_b32_e32 v225, v19
	v_pk_add_f32 v[222:223], v[226:227], v[222:223]
	v_mov_b32_e32 v224, v18
	v_add_f32_e32 v221, v222, v223
	ds_bpermute_b32 v222, v216, v221
	v_mov_b32_e32 v226, v11
	s_waitcnt lgkmcnt(0)
	v_add_f32_e32 v221, v221, v222
	v_mov_b32_e32 v222, v221
	s_nop 1
	v_permlane32_swap_b32 v221, v222
	s_waitcnt lgkmcnt(0)
	v_add_f32_e32 v221, v221, v222
	v_fmamk_f32 v223, v221, 0xbc800000, v21
	v_fmac_f32_e32 v225, 0xbc800000, v221
	v_fmamk_f32 v222, v221, 0xbc800000, v20
	v_fmac_f32_e32 v224, 0xbc800000, v221
	v_mul_f32_e32 v225, v225, v225
	v_mul_f32_e32 v223, v223, v223
	v_fmac_f32_e32 v225, v224, v224
	v_fmac_f32_e32 v223, v222, v222
	v_add_f32_e32 v222, v225, v223
	v_fmamk_f32 v224, v221, 0xbc800000, v13
	v_mov_b32_e32 v225, v10
	v_fmac_f32_e32 v226, 0xbc800000, v221
	v_fmamk_f32 v223, v221, 0xbc800000, v12
	v_fmac_f32_e32 v225, 0xbc800000, v221
	v_mul_f32_e32 v226, v226, v226
	v_mul_f32_e32 v224, v224, v224
	v_fmac_f32_e32 v226, v225, v225
	v_fmac_f32_e32 v224, v223, v223
	v_add_f32_e32 v223, v226, v224
	v_mov_b32_e32 v226, v7
	v_fmamk_f32 v224, v221, 0xbc800000, v9
	v_mov_b32_e32 v225, v6
	v_fmac_f32_e32 v226, 0xbc800000, v221
	v_add_f32_e32 v222, v222, v223
	v_fmamk_f32 v223, v221, 0xbc800000, v8
	v_fmac_f32_e32 v225, 0xbc800000, v221
	v_mul_f32_e32 v226, v226, v226
	v_mul_f32_e32 v224, v224, v224
	v_fmac_f32_e32 v226, v225, v225
	v_fmac_f32_e32 v224, v223, v223
	v_add_f32_e32 v223, v226, v224
	v_mov_b32_e32 v226, v3
	v_fmamk_f32 v224, v221, 0xbc800000, v5
	v_mov_b32_e32 v225, v2
	v_fmac_f32_e32 v226, 0xbc800000, v221
	v_add_f32_e32 v222, v223, v222
	v_fmamk_f32 v223, v221, 0xbc800000, v4
	v_fmac_f32_e32 v225, 0xbc800000, v221
	v_mul_f32_e32 v226, v226, v226
	v_mul_f32_e32 v224, v224, v224
	v_fmac_f32_e32 v226, v225, v225
	v_fmac_f32_e32 v224, v223, v223
	v_add_f32_e32 v223, v226, v224
	v_add_f32_e32 v222, v223, v222
	ds_bpermute_b32 v216, v216, v222
	s_waitcnt lgkmcnt(0)
	v_add_f32_e32 v216, v222, v216
	ds_bpermute_b32 v220, v220, v216
	s_and_saveexec_b64 s[0:1], vcc
	s_cbranch_execz .LBB0_1280
	s_lshl_b32 s4, s13, 11
	s_add_i32 s2, s2, s4
	v_mul_f32_e32 v222, 0x3c800000, v221
	v_lshl_add_u32 v1, v1, 5, s2
	s_waitcnt lgkmcnt(0)
	v_add_f32_e32 v223, v216, v220
	ds_write_b64 v1, v[222:223] offset:5632
